# loop counter/pointer bumps and exit test hoisted from behind the last MFMA segment into the preceding load segment (4-phase loops)
# speedup vs baseline: 1.0022x; 1.0022x over previous
.LBB0_98:
	v_mov_b64_e32 v[2:3], 0x5ac
	s_ashr_i32 s9, s8, 31
	v_cmp_lt_i64_e32 vcc, s[10:11], v[2:3]
	s_lshl_b64 s[10:11], s[8:9], 19
	s_add_u32 s10, s54, s10
	s_addc_u32 s11, s55, s11
	s_and_b64 s[12:13], vcc, exec
	s_cselect_b32 s9, s11, s15
	s_cselect_b32 s40, s10, s14
	s_ashr_i32 s7, s6, 31
	s_lshl_b64 s[12:13], s[6:7], 19
	s_add_u32 s12, s23, s12
	s_addc_u32 s13, s24, s13
	s_and_b64 s[18:19], vcc, exec
	s_cselect_b32 s7, s13, s17
	s_cselect_b32 s41, s12, s16
	s_add_u32 s14, s14, 0x40080
	s_addc_u32 s15, s15, 0
	s_add_u32 s42, s16, 0x100
	s_addc_u32 s43, s17, 0
	s_mov_b32 s44, -2
	s_add_u32 s16, s14, 0xfffc0080
	s_addc_u32 s17, s15, -1
	s_add_i32 s45, 0, 0x10000
	v_add_u32_e32 v249, s45, v139
	ds_read_b128 v[142:145], v249
	ds_read_b128 v[146:149], v249 offset:1024
	ds_read_b128 v[150:153], v249 offset:2048
	ds_read_b128 v[154:157], v249 offset:3072
	s_cmp_eq_u32 s44, 12
	s_cselect_b32 s19, s9, s17
	s_cselect_b32 s18, s40, s16
	s_cselect_b32 s17, s7, s43
	s_cselect_b32 s16, s41, s42
	s_add_i32 s48, 0, 0x14000
	ds_read_b128 v[204:207], v249 offset:16384
	ds_read_b128 v[208:211], v249 offset:17408
	ds_read_b128 v[212:215], v249 offset:18432
	ds_read_b128 v[216:219], v249 offset:19456
	s_add_i32 m0, s26, 0xc000
	ds_read_b128 v[158:161], v140
	ds_read_b128 v[162:165], v140 offset:1024
	ds_read_b128 v[166:169], v140 offset:2048
	ds_read_b128 v[170:173], v140 offset:3072
	ds_read_b128 v[174:177], v140 offset:4096
	ds_read_b128 v[178:181], v140 offset:5120
	ds_read_b128 v[182:185], v140 offset:6144
	ds_read_b128 v[186:189], v140 offset:7168
	global_load_lds_dwordx4 v134, s[14:15]
	s_add_i32 m0, s26, 0xe000
	s_nop 0
	global_load_lds_dwordx4 v136, s[14:15]
	s_waitcnt vmcnt(8) lgkmcnt(0)
	s_barrier
	s_setprio 1
	v_mfma_f32_16x16x32_bf16 v[126:129], v[142:145], v[158:161], 0
	v_mfma_f32_16x16x32_bf16 v[122:125], v[150:153], v[158:161], 0
	v_mfma_f32_16x16x32_bf16 v[110:113], v[142:145], v[166:169], 0
	v_mfma_f32_16x16x32_bf16 v[106:109], v[150:153], v[166:169], 0
	v_mfma_f32_16x16x32_bf16 v[94:97], v[142:145], v[174:177], 0
	v_mfma_f32_16x16x32_bf16 v[90:93], v[150:153], v[174:177], 0
	v_mfma_f32_16x16x32_bf16 v[78:81], v[142:145], v[182:185], 0
	v_mfma_f32_16x16x32_bf16 v[74:77], v[150:153], v[182:185], 0
	v_mfma_f32_16x16x32_bf16 v[126:129], v[146:149], v[162:165], v[126:129]
	v_mfma_f32_16x16x32_bf16 v[122:125], v[154:157], v[162:165], v[122:125]
	v_mfma_f32_16x16x32_bf16 v[110:113], v[146:149], v[170:173], v[110:113]
	v_mfma_f32_16x16x32_bf16 v[106:109], v[154:157], v[170:173], v[106:109]
	v_mfma_f32_16x16x32_bf16 v[94:97], v[146:149], v[178:181], v[94:97]
	v_mfma_f32_16x16x32_bf16 v[90:93], v[154:157], v[178:181], v[90:93]
	v_mfma_f32_16x16x32_bf16 v[78:81], v[146:149], v[186:189], v[78:81]
	v_mfma_f32_16x16x32_bf16 v[74:77], v[154:157], v[186:189], v[74:77]
	v_mfma_f32_16x16x32_bf16 v[118:121], v[204:207], v[158:161], 0
	v_mfma_f32_16x16x32_bf16 v[114:117], v[212:215], v[158:161], 0
	v_mfma_f32_16x16x32_bf16 v[102:105], v[204:207], v[166:169], 0
	v_mfma_f32_16x16x32_bf16 v[98:101], v[212:215], v[166:169], 0
	v_mfma_f32_16x16x32_bf16 v[86:89], v[204:207], v[174:177], 0
	v_mfma_f32_16x16x32_bf16 v[82:85], v[212:215], v[174:177], 0
	v_mfma_f32_16x16x32_bf16 v[70:73], v[204:207], v[182:185], 0
	v_mfma_f32_16x16x32_bf16 v[66:69], v[212:215], v[182:185], 0
	v_mfma_f32_16x16x32_bf16 v[118:121], v[208:211], v[162:165], v[118:121]
	v_mfma_f32_16x16x32_bf16 v[114:117], v[216:219], v[162:165], v[114:117]
	v_mfma_f32_16x16x32_bf16 v[102:105], v[208:211], v[170:173], v[102:105]
	v_mfma_f32_16x16x32_bf16 v[98:101], v[216:219], v[170:173], v[98:101]
	v_mfma_f32_16x16x32_bf16 v[86:89], v[208:211], v[178:181], v[86:89]
	v_mfma_f32_16x16x32_bf16 v[82:85], v[216:219], v[178:181], v[82:85]
	v_mfma_f32_16x16x32_bf16 v[70:73], v[208:211], v[186:189], v[70:73]
	v_mfma_f32_16x16x32_bf16 v[66:69], v[216:219], v[186:189], v[66:69]
	s_setprio 0
	s_barrier
	ds_read_b128 v[158:161], v140 offset:16384
	ds_read_b128 v[162:165], v140 offset:17408
	ds_read_b128 v[166:169], v140 offset:18432
	ds_read_b128 v[170:173], v140 offset:19456
	ds_read_b128 v[174:177], v140 offset:20480
	ds_read_b128 v[178:181], v140 offset:21504
	ds_read_b128 v[182:185], v140 offset:22528
	ds_read_b128 v[186:189], v140 offset:23552
	s_add_i32 s45, s45, s25
	s_mov_b32 m0, s45
	s_nop 0
	global_load_lds_dwordx4 v132, s[16:17]
	s_add_i32 m0, s45, 0x2000
	s_nop 0
	global_load_lds_dwordx4 v130, s[16:17]
	s_mov_b32 m0, s26
	s_add_u32 s98, s18, 0x80
	s_addc_u32 s99, s19, 0
	global_load_lds_dwordx4 v132, s[18:19]
	s_mov_b32 m0, s27
	s_nop 0
	global_load_lds_dwordx4 v130, s[18:19]
	s_add_u32 s46, s16, 0x40000
	s_addc_u32 s47, s17, 0
	s_add_i32 s45, s48, s25
	s_mov_b32 m0, s45
	s_nop 0
	global_load_lds_dwordx4 v132, s[46:47]
	s_add_i32 m0, s45, 0x2000
	s_nop 0
	global_load_lds_dwordx4 v130, s[46:47]
	s_waitcnt vmcnt(8) lgkmcnt(0)
	s_barrier
	s_setprio 1
	v_mfma_f32_16x16x32_bf16 v[62:65], v[142:145], v[158:161], 0
	v_mfma_f32_16x16x32_bf16 v[58:61], v[150:153], v[158:161], 0
	v_mfma_f32_16x16x32_bf16 v[46:49], v[142:145], v[166:169], 0
	v_mfma_f32_16x16x32_bf16 v[42:45], v[150:153], v[166:169], 0
	v_mfma_f32_16x16x32_bf16 v[30:33], v[142:145], v[174:177], 0
	v_mfma_f32_16x16x32_bf16 v[26:29], v[150:153], v[174:177], 0
	v_mfma_f32_16x16x32_bf16 v[14:17], v[142:145], v[182:185], 0
	v_mfma_f32_16x16x32_bf16 v[10:13], v[150:153], v[182:185], 0
	v_mfma_f32_16x16x32_bf16 v[62:65], v[146:149], v[162:165], v[62:65]
	v_mfma_f32_16x16x32_bf16 v[58:61], v[154:157], v[162:165], v[58:61]
	v_mfma_f32_16x16x32_bf16 v[46:49], v[146:149], v[170:173], v[46:49]
	v_mfma_f32_16x16x32_bf16 v[42:45], v[154:157], v[170:173], v[42:45]
	v_mfma_f32_16x16x32_bf16 v[30:33], v[146:149], v[178:181], v[30:33]
	v_mfma_f32_16x16x32_bf16 v[26:29], v[154:157], v[178:181], v[26:29]
	v_mfma_f32_16x16x32_bf16 v[14:17], v[146:149], v[186:189], v[14:17]
	v_mfma_f32_16x16x32_bf16 v[10:13], v[154:157], v[186:189], v[10:13]
	v_mfma_f32_16x16x32_bf16 v[54:57], v[204:207], v[158:161], 0
	v_mfma_f32_16x16x32_bf16 v[50:53], v[212:215], v[158:161], 0
	v_mfma_f32_16x16x32_bf16 v[38:41], v[204:207], v[166:169], 0
	v_mfma_f32_16x16x32_bf16 v[34:37], v[212:215], v[166:169], 0
	v_mfma_f32_16x16x32_bf16 v[22:25], v[204:207], v[174:177], 0
	v_mfma_f32_16x16x32_bf16 v[18:21], v[212:215], v[174:177], 0
	v_mfma_f32_16x16x32_bf16 v[6:9], v[204:207], v[182:185], 0
	v_mfma_f32_16x16x32_bf16 v[2:5], v[212:215], v[182:185], 0
	v_mfma_f32_16x16x32_bf16 v[54:57], v[208:211], v[162:165], v[54:57]
	v_mfma_f32_16x16x32_bf16 v[50:53], v[216:219], v[162:165], v[50:53]
	v_mfma_f32_16x16x32_bf16 v[38:41], v[208:211], v[170:173], v[38:41]
	v_mfma_f32_16x16x32_bf16 v[34:37], v[216:219], v[170:173], v[34:37]
	v_mfma_f32_16x16x32_bf16 v[22:25], v[208:211], v[178:181], v[22:25]
	v_mfma_f32_16x16x32_bf16 v[18:21], v[216:219], v[178:181], v[18:21]
	v_mfma_f32_16x16x32_bf16 v[6:9], v[208:211], v[186:189], v[6:9]
	v_mfma_f32_16x16x32_bf16 v[2:5], v[216:219], v[186:189], v[2:5]
	s_setprio 0
	s_barrier
	s_add_i32 s45, 0, 0x18000
	ds_read_b128 v[142:145], v249 offset:32768
	ds_read_b128 v[146:149], v249 offset:33792
	ds_read_b128 v[150:153], v249 offset:34816
	ds_read_b128 v[154:157], v249 offset:35840
	s_add_u32 s18, s18, 0x40000
	s_addc_u32 s19, s19, 0
	s_mov_b32 m0, s28
	ds_read_b128 v[158:161], v140 offset:32768
	ds_read_b128 v[162:165], v140 offset:33792
	ds_read_b128 v[166:169], v140 offset:34816
	ds_read_b128 v[170:173], v140 offset:35840
	ds_read_b128 v[174:177], v140 offset:36864
	ds_read_b128 v[178:181], v140 offset:37888
	ds_read_b128 v[182:185], v140 offset:38912
	ds_read_b128 v[186:189], v140 offset:39936
	global_load_lds_dwordx4 v132, s[18:19]
	s_mov_b32 m0, s29
	s_nop 0
	global_load_lds_dwordx4 v130, s[18:19]
	s_add_i32 s18, 0, 0x1c000
	ds_read_b128 v[204:207], v249 offset:49152
	ds_read_b128 v[208:211], v249 offset:50176
	ds_read_b128 v[212:215], v249 offset:51200
	ds_read_b128 v[216:219], v249 offset:52224
	s_waitcnt vmcnt(8) lgkmcnt(0)
	s_barrier
	s_setprio 1
	v_mfma_f32_16x16x32_bf16 v[126:129], v[142:145], v[158:161], v[126:129]
	v_mfma_f32_16x16x32_bf16 v[122:125], v[150:153], v[158:161], v[122:125]
	v_mfma_f32_16x16x32_bf16 v[110:113], v[142:145], v[166:169], v[110:113]
	v_mfma_f32_16x16x32_bf16 v[106:109], v[150:153], v[166:169], v[106:109]
	v_mfma_f32_16x16x32_bf16 v[94:97], v[142:145], v[174:177], v[94:97]
	v_mfma_f32_16x16x32_bf16 v[90:93], v[150:153], v[174:177], v[90:93]
	v_mfma_f32_16x16x32_bf16 v[78:81], v[142:145], v[182:185], v[78:81]
	v_mfma_f32_16x16x32_bf16 v[74:77], v[150:153], v[182:185], v[74:77]
	v_mfma_f32_16x16x32_bf16 v[126:129], v[146:149], v[162:165], v[126:129]
	v_mfma_f32_16x16x32_bf16 v[122:125], v[154:157], v[162:165], v[122:125]
	v_mfma_f32_16x16x32_bf16 v[110:113], v[146:149], v[170:173], v[110:113]
	v_mfma_f32_16x16x32_bf16 v[106:109], v[154:157], v[170:173], v[106:109]
	v_mfma_f32_16x16x32_bf16 v[94:97], v[146:149], v[178:181], v[94:97]
	v_mfma_f32_16x16x32_bf16 v[90:93], v[154:157], v[178:181], v[90:93]
	v_mfma_f32_16x16x32_bf16 v[78:81], v[146:149], v[186:189], v[78:81]
	v_mfma_f32_16x16x32_bf16 v[74:77], v[154:157], v[186:189], v[74:77]
	v_mfma_f32_16x16x32_bf16 v[118:121], v[204:207], v[158:161], v[118:121]
	v_mfma_f32_16x16x32_bf16 v[114:117], v[212:215], v[158:161], v[114:117]
	v_mfma_f32_16x16x32_bf16 v[102:105], v[204:207], v[166:169], v[102:105]
	v_mfma_f32_16x16x32_bf16 v[98:101], v[212:215], v[166:169], v[98:101]
	v_mfma_f32_16x16x32_bf16 v[86:89], v[204:207], v[174:177], v[86:89]
	v_mfma_f32_16x16x32_bf16 v[82:85], v[212:215], v[174:177], v[82:85]
	v_mfma_f32_16x16x32_bf16 v[70:73], v[204:207], v[182:185], v[70:73]
	v_mfma_f32_16x16x32_bf16 v[66:69], v[212:215], v[182:185], v[66:69]
	v_mfma_f32_16x16x32_bf16 v[118:121], v[208:211], v[162:165], v[118:121]
	v_mfma_f32_16x16x32_bf16 v[114:117], v[216:219], v[162:165], v[114:117]
	v_mfma_f32_16x16x32_bf16 v[102:105], v[208:211], v[170:173], v[102:105]
	v_mfma_f32_16x16x32_bf16 v[98:101], v[216:219], v[170:173], v[98:101]
	v_mfma_f32_16x16x32_bf16 v[86:89], v[208:211], v[178:181], v[86:89]
	v_mfma_f32_16x16x32_bf16 v[82:85], v[216:219], v[178:181], v[82:85]
	v_mfma_f32_16x16x32_bf16 v[70:73], v[208:211], v[186:189], v[70:73]
	v_mfma_f32_16x16x32_bf16 v[66:69], v[216:219], v[186:189], v[66:69]
	s_setprio 0
	s_barrier
	ds_read_b128 v[158:161], v140 offset:49152
	ds_read_b128 v[162:165], v140 offset:50176
	ds_read_b128 v[166:169], v140 offset:51200
	ds_read_b128 v[170:173], v140 offset:52224
	ds_read_b128 v[174:177], v140 offset:53248
	ds_read_b128 v[178:181], v140 offset:54272
	ds_read_b128 v[182:185], v140 offset:55296
	ds_read_b128 v[186:189], v140 offset:56320
	s_add_i32 s19, s45, s25
	s_mov_b32 m0, s19
	s_add_u32 vcc_lo, s16, 0x80
	s_addc_u32 vcc_hi, s17, 0
	global_load_lds_dwordx4 v132, vcc
	s_add_i32 m0, s19, 0x2000
	s_nop 0
	global_load_lds_dwordx4 v130, vcc
	s_mov_b32 m0, s30
	s_nop 0
	global_load_lds_dwordx4 v132, s[98:99]
	s_mov_b32 m0, s31
	s_nop 0
	global_load_lds_dwordx4 v130, s[98:99]
	s_add_u32 s16, s16, 0x40080
	s_addc_u32 s17, s17, 0
	s_add_i32 s18, s18, s25
	s_mov_b32 m0, s18
	s_nop 0
	global_load_lds_dwordx4 v132, s[16:17]
	s_add_i32 m0, s18, 0x2000
	s_nop 0
	global_load_lds_dwordx4 v130, s[16:17]
	s_add_i32 s44, s44, 2
	s_add_u32 s14, s14, 0x100
	s_addc_u32 s15, s15, 0
	s_add_u32 s42, s42, 0x100
	s_addc_u32 s43, s43, 0
	s_cmp_gt_u32 s44, 13
	s_waitcnt vmcnt(8) lgkmcnt(0)
	s_barrier
	s_setprio 1
	v_mfma_f32_16x16x32_bf16 v[62:65], v[142:145], v[158:161], v[62:65]
	v_mfma_f32_16x16x32_bf16 v[58:61], v[150:153], v[158:161], v[58:61]
	v_mfma_f32_16x16x32_bf16 v[46:49], v[142:145], v[166:169], v[46:49]
	v_mfma_f32_16x16x32_bf16 v[42:45], v[150:153], v[166:169], v[42:45]
	v_mfma_f32_16x16x32_bf16 v[30:33], v[142:145], v[174:177], v[30:33]
	v_mfma_f32_16x16x32_bf16 v[26:29], v[150:153], v[174:177], v[26:29]
	v_mfma_f32_16x16x32_bf16 v[14:17], v[142:145], v[182:185], v[14:17]
	v_mfma_f32_16x16x32_bf16 v[10:13], v[150:153], v[182:185], v[10:13]
	v_mfma_f32_16x16x32_bf16 v[62:65], v[146:149], v[162:165], v[62:65]
	v_mfma_f32_16x16x32_bf16 v[58:61], v[154:157], v[162:165], v[58:61]
	v_mfma_f32_16x16x32_bf16 v[46:49], v[146:149], v[170:173], v[46:49]
	v_mfma_f32_16x16x32_bf16 v[42:45], v[154:157], v[170:173], v[42:45]
	v_mfma_f32_16x16x32_bf16 v[30:33], v[146:149], v[178:181], v[30:33]
	v_mfma_f32_16x16x32_bf16 v[26:29], v[154:157], v[178:181], v[26:29]
	v_mfma_f32_16x16x32_bf16 v[14:17], v[146:149], v[186:189], v[14:17]
	v_mfma_f32_16x16x32_bf16 v[10:13], v[154:157], v[186:189], v[10:13]
	v_mfma_f32_16x16x32_bf16 v[54:57], v[204:207], v[158:161], v[54:57]
	v_mfma_f32_16x16x32_bf16 v[50:53], v[212:215], v[158:161], v[50:53]
	v_mfma_f32_16x16x32_bf16 v[38:41], v[204:207], v[166:169], v[38:41]
	v_mfma_f32_16x16x32_bf16 v[34:37], v[212:215], v[166:169], v[34:37]
	v_mfma_f32_16x16x32_bf16 v[22:25], v[204:207], v[174:177], v[22:25]
	v_mfma_f32_16x16x32_bf16 v[18:21], v[212:215], v[174:177], v[18:21]
	v_mfma_f32_16x16x32_bf16 v[6:9], v[204:207], v[182:185], v[6:9]
	v_mfma_f32_16x16x32_bf16 v[2:5], v[212:215], v[182:185], v[2:5]
	v_mfma_f32_16x16x32_bf16 v[54:57], v[208:211], v[162:165], v[54:57]
	v_mfma_f32_16x16x32_bf16 v[50:53], v[216:219], v[162:165], v[50:53]
	v_mfma_f32_16x16x32_bf16 v[38:41], v[208:211], v[170:173], v[38:41]
	v_mfma_f32_16x16x32_bf16 v[34:37], v[216:219], v[170:173], v[34:37]
	v_mfma_f32_16x16x32_bf16 v[22:25], v[208:211], v[178:181], v[22:25]
	v_mfma_f32_16x16x32_bf16 v[18:21], v[216:219], v[178:181], v[18:21]
	v_mfma_f32_16x16x32_bf16 v[6:9], v[208:211], v[186:189], v[6:9]
	v_mfma_f32_16x16x32_bf16 v[2:5], v[216:219], v[186:189], v[2:5]
	s_setprio 0
	s_barrier
.LBB0_99:
	s_add_u32 s16, s14, 0xfffc0080
	s_addc_u32 s17, s15, -1
	s_add_i32 s45, 0, 0x10000
	v_add_u32_e32 v249, s45, v139
	ds_read_b128 v[142:145], v249
	ds_read_b128 v[146:149], v249 offset:1024
	ds_read_b128 v[150:153], v249 offset:2048
	ds_read_b128 v[154:157], v249 offset:3072
	s_cmp_eq_u32 s44, 12
	s_cselect_b32 s19, s9, s17
	s_cselect_b32 s18, s40, s16
	s_cselect_b32 s17, s7, s43
	s_cselect_b32 s16, s41, s42
	s_add_i32 s48, 0, 0x14000
	ds_read_b128 v[204:207], v249 offset:16384
	ds_read_b128 v[208:211], v249 offset:17408
	ds_read_b128 v[212:215], v249 offset:18432
	ds_read_b128 v[216:219], v249 offset:19456
	s_add_i32 m0, s26, 0xc000
	ds_read_b128 v[158:161], v140
	ds_read_b128 v[162:165], v140 offset:1024
	ds_read_b128 v[166:169], v140 offset:2048
	ds_read_b128 v[170:173], v140 offset:3072
	ds_read_b128 v[174:177], v140 offset:4096
	ds_read_b128 v[178:181], v140 offset:5120
	ds_read_b128 v[182:185], v140 offset:6144
	ds_read_b128 v[186:189], v140 offset:7168
	global_load_lds_dwordx4 v134, s[14:15]
	s_add_i32 m0, s26, 0xe000
	s_nop 0
	global_load_lds_dwordx4 v136, s[14:15]
	s_waitcnt vmcnt(8) lgkmcnt(0)
	s_barrier
	s_setprio 1
	v_mfma_f32_16x16x32_bf16 v[126:129], v[142:145], v[158:161], v[126:129]
	v_mfma_f32_16x16x32_bf16 v[122:125], v[150:153], v[158:161], v[122:125]
	v_mfma_f32_16x16x32_bf16 v[110:113], v[142:145], v[166:169], v[110:113]
	v_mfma_f32_16x16x32_bf16 v[106:109], v[150:153], v[166:169], v[106:109]
	v_mfma_f32_16x16x32_bf16 v[94:97], v[142:145], v[174:177], v[94:97]
	v_mfma_f32_16x16x32_bf16 v[90:93], v[150:153], v[174:177], v[90:93]
	v_mfma_f32_16x16x32_bf16 v[78:81], v[142:145], v[182:185], v[78:81]
	v_mfma_f32_16x16x32_bf16 v[74:77], v[150:153], v[182:185], v[74:77]
	v_mfma_f32_16x16x32_bf16 v[126:129], v[146:149], v[162:165], v[126:129]
	v_mfma_f32_16x16x32_bf16 v[122:125], v[154:157], v[162:165], v[122:125]
	v_mfma_f32_16x16x32_bf16 v[110:113], v[146:149], v[170:173], v[110:113]
	v_mfma_f32_16x16x32_bf16 v[106:109], v[154:157], v[170:173], v[106:109]
	v_mfma_f32_16x16x32_bf16 v[94:97], v[146:149], v[178:181], v[94:97]
	v_mfma_f32_16x16x32_bf16 v[90:93], v[154:157], v[178:181], v[90:93]
	v_mfma_f32_16x16x32_bf16 v[78:81], v[146:149], v[186:189], v[78:81]
	v_mfma_f32_16x16x32_bf16 v[74:77], v[154:157], v[186:189], v[74:77]
	v_mfma_f32_16x16x32_bf16 v[118:121], v[204:207], v[158:161], v[118:121]
	v_mfma_f32_16x16x32_bf16 v[114:117], v[212:215], v[158:161], v[114:117]
	v_mfma_f32_16x16x32_bf16 v[102:105], v[204:207], v[166:169], v[102:105]
	v_mfma_f32_16x16x32_bf16 v[98:101], v[212:215], v[166:169], v[98:101]
	v_mfma_f32_16x16x32_bf16 v[86:89], v[204:207], v[174:177], v[86:89]
	v_mfma_f32_16x16x32_bf16 v[82:85], v[212:215], v[174:177], v[82:85]
	v_mfma_f32_16x16x32_bf16 v[70:73], v[204:207], v[182:185], v[70:73]
	v_mfma_f32_16x16x32_bf16 v[66:69], v[212:215], v[182:185], v[66:69]
	v_mfma_f32_16x16x32_bf16 v[118:121], v[208:211], v[162:165], v[118:121]
	v_mfma_f32_16x16x32_bf16 v[114:117], v[216:219], v[162:165], v[114:117]
	v_mfma_f32_16x16x32_bf16 v[102:105], v[208:211], v[170:173], v[102:105]
	v_mfma_f32_16x16x32_bf16 v[98:101], v[216:219], v[170:173], v[98:101]
	v_mfma_f32_16x16x32_bf16 v[86:89], v[208:211], v[178:181], v[86:89]
	v_mfma_f32_16x16x32_bf16 v[82:85], v[216:219], v[178:181], v[82:85]
	v_mfma_f32_16x16x32_bf16 v[70:73], v[208:211], v[186:189], v[70:73]
	v_mfma_f32_16x16x32_bf16 v[66:69], v[216:219], v[186:189], v[66:69]
	s_setprio 0
	s_barrier
	ds_read_b128 v[158:161], v140 offset:16384
	ds_read_b128 v[162:165], v140 offset:17408
	ds_read_b128 v[166:169], v140 offset:18432
	ds_read_b128 v[170:173], v140 offset:19456
	ds_read_b128 v[174:177], v140 offset:20480
	ds_read_b128 v[178:181], v140 offset:21504
	ds_read_b128 v[182:185], v140 offset:22528
	ds_read_b128 v[186:189], v140 offset:23552
	s_add_i32 s45, s45, s25
	s_mov_b32 m0, s45
	s_nop 0
	global_load_lds_dwordx4 v132, s[16:17]
	s_add_i32 m0, s45, 0x2000
	s_nop 0
	global_load_lds_dwordx4 v130, s[16:17]
	s_mov_b32 m0, s26
	s_add_u32 s98, s18, 0x80
	s_addc_u32 s99, s19, 0
	global_load_lds_dwordx4 v132, s[18:19]
	s_mov_b32 m0, s27
	s_nop 0
	global_load_lds_dwordx4 v130, s[18:19]
	s_add_u32 s46, s16, 0x40000
	s_addc_u32 s47, s17, 0
	s_add_i32 s45, s48, s25
	s_mov_b32 m0, s45
	s_nop 0
	global_load_lds_dwordx4 v132, s[46:47]
	s_add_i32 m0, s45, 0x2000
	s_nop 0
	global_load_lds_dwordx4 v130, s[46:47]
	s_waitcnt vmcnt(8) lgkmcnt(0)
	s_barrier
	s_setprio 1
	v_mfma_f32_16x16x32_bf16 v[62:65], v[142:145], v[158:161], v[62:65]
	v_mfma_f32_16x16x32_bf16 v[58:61], v[150:153], v[158:161], v[58:61]
	v_mfma_f32_16x16x32_bf16 v[46:49], v[142:145], v[166:169], v[46:49]
	v_mfma_f32_16x16x32_bf16 v[42:45], v[150:153], v[166:169], v[42:45]
	v_mfma_f32_16x16x32_bf16 v[30:33], v[142:145], v[174:177], v[30:33]
	v_mfma_f32_16x16x32_bf16 v[26:29], v[150:153], v[174:177], v[26:29]
	v_mfma_f32_16x16x32_bf16 v[14:17], v[142:145], v[182:185], v[14:17]
	v_mfma_f32_16x16x32_bf16 v[10:13], v[150:153], v[182:185], v[10:13]
	v_mfma_f32_16x16x32_bf16 v[62:65], v[146:149], v[162:165], v[62:65]
	v_mfma_f32_16x16x32_bf16 v[58:61], v[154:157], v[162:165], v[58:61]
	v_mfma_f32_16x16x32_bf16 v[46:49], v[146:149], v[170:173], v[46:49]
	v_mfma_f32_16x16x32_bf16 v[42:45], v[154:157], v[170:173], v[42:45]
	v_mfma_f32_16x16x32_bf16 v[30:33], v[146:149], v[178:181], v[30:33]
	v_mfma_f32_16x16x32_bf16 v[26:29], v[154:157], v[178:181], v[26:29]
	v_mfma_f32_16x16x32_bf16 v[14:17], v[146:149], v[186:189], v[14:17]
	v_mfma_f32_16x16x32_bf16 v[10:13], v[154:157], v[186:189], v[10:13]
	v_mfma_f32_16x16x32_bf16 v[54:57], v[204:207], v[158:161], v[54:57]
	v_mfma_f32_16x16x32_bf16 v[50:53], v[212:215], v[158:161], v[50:53]
	v_mfma_f32_16x16x32_bf16 v[38:41], v[204:207], v[166:169], v[38:41]
	v_mfma_f32_16x16x32_bf16 v[34:37], v[212:215], v[166:169], v[34:37]
	v_mfma_f32_16x16x32_bf16 v[22:25], v[204:207], v[174:177], v[22:25]
	v_mfma_f32_16x16x32_bf16 v[18:21], v[212:215], v[174:177], v[18:21]
	v_mfma_f32_16x16x32_bf16 v[6:9], v[204:207], v[182:185], v[6:9]
	v_mfma_f32_16x16x32_bf16 v[2:5], v[212:215], v[182:185], v[2:5]
	v_mfma_f32_16x16x32_bf16 v[54:57], v[208:211], v[162:165], v[54:57]
	v_mfma_f32_16x16x32_bf16 v[50:53], v[216:219], v[162:165], v[50:53]
	v_mfma_f32_16x16x32_bf16 v[38:41], v[208:211], v[170:173], v[38:41]
	v_mfma_f32_16x16x32_bf16 v[34:37], v[216:219], v[170:173], v[34:37]
	v_mfma_f32_16x16x32_bf16 v[22:25], v[208:211], v[178:181], v[22:25]
	v_mfma_f32_16x16x32_bf16 v[18:21], v[216:219], v[178:181], v[18:21]
	v_mfma_f32_16x16x32_bf16 v[6:9], v[208:211], v[186:189], v[6:9]
	v_mfma_f32_16x16x32_bf16 v[2:5], v[216:219], v[186:189], v[2:5]
	s_setprio 0
	s_barrier
	s_add_i32 s45, 0, 0x18000
	ds_read_b128 v[142:145], v249 offset:32768
	ds_read_b128 v[146:149], v249 offset:33792
	ds_read_b128 v[150:153], v249 offset:34816
	ds_read_b128 v[154:157], v249 offset:35840
	s_add_u32 s18, s18, 0x40000
	s_addc_u32 s19, s19, 0
	s_mov_b32 m0, s28
	ds_read_b128 v[158:161], v140 offset:32768
	ds_read_b128 v[162:165], v140 offset:33792
	ds_read_b128 v[166:169], v140 offset:34816
	ds_read_b128 v[170:173], v140 offset:35840
	ds_read_b128 v[174:177], v140 offset:36864
	ds_read_b128 v[178:181], v140 offset:37888
	ds_read_b128 v[182:185], v140 offset:38912
	ds_read_b128 v[186:189], v140 offset:39936
	global_load_lds_dwordx4 v132, s[18:19]
	s_mov_b32 m0, s29
	s_nop 0
	global_load_lds_dwordx4 v130, s[18:19]
	s_add_i32 s18, 0, 0x1c000
	ds_read_b128 v[204:207], v249 offset:49152
	ds_read_b128 v[208:211], v249 offset:50176
	ds_read_b128 v[212:215], v249 offset:51200
	ds_read_b128 v[216:219], v249 offset:52224
	s_waitcnt vmcnt(8) lgkmcnt(0)
	s_barrier
	s_setprio 1
	v_mfma_f32_16x16x32_bf16 v[126:129], v[142:145], v[158:161], v[126:129]
	v_mfma_f32_16x16x32_bf16 v[122:125], v[150:153], v[158:161], v[122:125]
	v_mfma_f32_16x16x32_bf16 v[110:113], v[142:145], v[166:169], v[110:113]
	v_mfma_f32_16x16x32_bf16 v[106:109], v[150:153], v[166:169], v[106:109]
	v_mfma_f32_16x16x32_bf16 v[94:97], v[142:145], v[174:177], v[94:97]
	v_mfma_f32_16x16x32_bf16 v[90:93], v[150:153], v[174:177], v[90:93]
	v_mfma_f32_16x16x32_bf16 v[78:81], v[142:145], v[182:185], v[78:81]
	v_mfma_f32_16x16x32_bf16 v[74:77], v[150:153], v[182:185], v[74:77]
	v_mfma_f32_16x16x32_bf16 v[126:129], v[146:149], v[162:165], v[126:129]
	v_mfma_f32_16x16x32_bf16 v[122:125], v[154:157], v[162:165], v[122:125]
	v_mfma_f32_16x16x32_bf16 v[110:113], v[146:149], v[170:173], v[110:113]
	v_mfma_f32_16x16x32_bf16 v[106:109], v[154:157], v[170:173], v[106:109]
	v_mfma_f32_16x16x32_bf16 v[94:97], v[146:149], v[178:181], v[94:97]
	v_mfma_f32_16x16x32_bf16 v[90:93], v[154:157], v[178:181], v[90:93]
	v_mfma_f32_16x16x32_bf16 v[78:81], v[146:149], v[186:189], v[78:81]
	v_mfma_f32_16x16x32_bf16 v[74:77], v[154:157], v[186:189], v[74:77]
	v_mfma_f32_16x16x32_bf16 v[118:121], v[204:207], v[158:161], v[118:121]
	v_mfma_f32_16x16x32_bf16 v[114:117], v[212:215], v[158:161], v[114:117]
	v_mfma_f32_16x16x32_bf16 v[102:105], v[204:207], v[166:169], v[102:105]
	v_mfma_f32_16x16x32_bf16 v[98:101], v[212:215], v[166:169], v[98:101]
	v_mfma_f32_16x16x32_bf16 v[86:89], v[204:207], v[174:177], v[86:89]
	v_mfma_f32_16x16x32_bf16 v[82:85], v[212:215], v[174:177], v[82:85]
	v_mfma_f32_16x16x32_bf16 v[70:73], v[204:207], v[182:185], v[70:73]
	v_mfma_f32_16x16x32_bf16 v[66:69], v[212:215], v[182:185], v[66:69]
	v_mfma_f32_16x16x32_bf16 v[118:121], v[208:211], v[162:165], v[118:121]
	v_mfma_f32_16x16x32_bf16 v[114:117], v[216:219], v[162:165], v[114:117]
	v_mfma_f32_16x16x32_bf16 v[102:105], v[208:211], v[170:173], v[102:105]
	v_mfma_f32_16x16x32_bf16 v[98:101], v[216:219], v[170:173], v[98:101]
	v_mfma_f32_16x16x32_bf16 v[86:89], v[208:211], v[178:181], v[86:89]
	v_mfma_f32_16x16x32_bf16 v[82:85], v[216:219], v[178:181], v[82:85]
	v_mfma_f32_16x16x32_bf16 v[70:73], v[208:211], v[186:189], v[70:73]
	v_mfma_f32_16x16x32_bf16 v[66:69], v[216:219], v[186:189], v[66:69]
	s_setprio 0
	s_barrier
	ds_read_b128 v[158:161], v140 offset:49152
	ds_read_b128 v[162:165], v140 offset:50176
	ds_read_b128 v[166:169], v140 offset:51200
	ds_read_b128 v[170:173], v140 offset:52224
	ds_read_b128 v[174:177], v140 offset:53248
	ds_read_b128 v[178:181], v140 offset:54272
	ds_read_b128 v[182:185], v140 offset:55296
	ds_read_b128 v[186:189], v140 offset:56320
	s_add_i32 s19, s45, s25
	s_mov_b32 m0, s19
	s_add_u32 vcc_lo, s16, 0x80
	s_addc_u32 vcc_hi, s17, 0
	global_load_lds_dwordx4 v132, vcc
	s_add_i32 m0, s19, 0x2000
	s_nop 0
	global_load_lds_dwordx4 v130, vcc
	s_mov_b32 m0, s30
	s_nop 0
	global_load_lds_dwordx4 v132, s[98:99]
	s_mov_b32 m0, s31
	s_nop 0
	global_load_lds_dwordx4 v130, s[98:99]
	s_add_u32 s16, s16, 0x40080
	s_addc_u32 s17, s17, 0
	s_add_i32 s18, s18, s25
	s_mov_b32 m0, s18
	s_nop 0
	global_load_lds_dwordx4 v132, s[16:17]
	s_add_i32 m0, s18, 0x2000
	s_nop 0
	global_load_lds_dwordx4 v130, s[16:17]
	s_add_i32 s44, s44, 2
	s_add_u32 s14, s14, 0x100
	s_addc_u32 s15, s15, 0
	s_add_u32 s42, s42, 0x100
	s_addc_u32 s43, s43, 0
	s_cmp_gt_u32 s44, 13
	s_waitcnt vmcnt(8) lgkmcnt(0)
	s_barrier
	s_setprio 1
	v_mfma_f32_16x16x32_bf16 v[62:65], v[142:145], v[158:161], v[62:65]
	v_mfma_f32_16x16x32_bf16 v[58:61], v[150:153], v[158:161], v[58:61]
	v_mfma_f32_16x16x32_bf16 v[46:49], v[142:145], v[166:169], v[46:49]
	v_mfma_f32_16x16x32_bf16 v[42:45], v[150:153], v[166:169], v[42:45]
	v_mfma_f32_16x16x32_bf16 v[30:33], v[142:145], v[174:177], v[30:33]
	v_mfma_f32_16x16x32_bf16 v[26:29], v[150:153], v[174:177], v[26:29]
	v_mfma_f32_16x16x32_bf16 v[14:17], v[142:145], v[182:185], v[14:17]
	v_mfma_f32_16x16x32_bf16 v[10:13], v[150:153], v[182:185], v[10:13]
	v_mfma_f32_16x16x32_bf16 v[62:65], v[146:149], v[162:165], v[62:65]
	v_mfma_f32_16x16x32_bf16 v[58:61], v[154:157], v[162:165], v[58:61]
	v_mfma_f32_16x16x32_bf16 v[46:49], v[146:149], v[170:173], v[46:49]
	v_mfma_f32_16x16x32_bf16 v[42:45], v[154:157], v[170:173], v[42:45]
	v_mfma_f32_16x16x32_bf16 v[30:33], v[146:149], v[178:181], v[30:33]
	v_mfma_f32_16x16x32_bf16 v[26:29], v[154:157], v[178:181], v[26:29]
	v_mfma_f32_16x16x32_bf16 v[14:17], v[146:149], v[186:189], v[14:17]
	v_mfma_f32_16x16x32_bf16 v[10:13], v[154:157], v[186:189], v[10:13]
	v_mfma_f32_16x16x32_bf16 v[54:57], v[204:207], v[158:161], v[54:57]
	v_mfma_f32_16x16x32_bf16 v[50:53], v[212:215], v[158:161], v[50:53]
	v_mfma_f32_16x16x32_bf16 v[38:41], v[204:207], v[166:169], v[38:41]
	v_mfma_f32_16x16x32_bf16 v[34:37], v[212:215], v[166:169], v[34:37]
	v_mfma_f32_16x16x32_bf16 v[22:25], v[204:207], v[174:177], v[22:25]
	v_mfma_f32_16x16x32_bf16 v[18:21], v[212:215], v[174:177], v[18:21]
	v_mfma_f32_16x16x32_bf16 v[6:9], v[204:207], v[182:185], v[6:9]
	v_mfma_f32_16x16x32_bf16 v[2:5], v[212:215], v[182:185], v[2:5]
	v_mfma_f32_16x16x32_bf16 v[54:57], v[208:211], v[162:165], v[54:57]
	v_mfma_f32_16x16x32_bf16 v[50:53], v[216:219], v[162:165], v[50:53]
	v_mfma_f32_16x16x32_bf16 v[38:41], v[208:211], v[170:173], v[38:41]
	v_mfma_f32_16x16x32_bf16 v[34:37], v[216:219], v[170:173], v[34:37]
	v_mfma_f32_16x16x32_bf16 v[22:25], v[208:211], v[178:181], v[22:25]
	v_mfma_f32_16x16x32_bf16 v[18:21], v[216:219], v[178:181], v[18:21]
	v_mfma_f32_16x16x32_bf16 v[6:9], v[208:211], v[186:189], v[6:9]
	v_mfma_f32_16x16x32_bf16 v[2:5], v[216:219], v[186:189], v[2:5]
	s_setprio 0
	s_barrier
	s_cbranch_scc0 .LBB0_99
	v_lshl_add_u32 v141, s37, 8, v138
	v_lshl_add_u32 v141, v141, 2, 0
	v_add_u32_e32 v142, 0x20040, v141
	ds_read2_b32 v[144:145], v142 offset1:16
	v_pk_mul_f32 v[124:125], v[128:129], v[124:125]
	v_pk_mul_f32 v[122:123], v[126:127], v[122:123]
	v_pk_mul_f32 v[114:115], v[118:119], v[114:115]
	v_pk_mul_f32 v[116:117], v[120:121], v[116:117]
	s_waitcnt lgkmcnt(0)
	v_mul_f32_e32 v146, 0xbfb8aa3b, v144
	v_pk_mul_f32 v[148:149], v[126:127], v[146:147] op_sel_hi:[1,0]
	v_pk_mul_f32 v[126:127], v[128:129], v[146:147] op_sel_hi:[1,0]
	v_pk_mul_f32 v[128:129], v[118:119], v[146:147] op_sel_hi:[1,0]
	v_pk_mul_f32 v[118:119], v[120:121], v[146:147] op_sel_hi:[1,0]
	v_exp_f32_e32 v128, v128
	v_exp_f32_e32 v129, v129
	v_exp_f32_e32 v148, v148
	v_exp_f32_e32 v149, v149
	v_exp_f32_e32 v126, v126
	v_exp_f32_e32 v127, v127
	v_exp_f32_e32 v118, v118
	v_exp_f32_e32 v119, v119
	v_pk_add_f32 v[128:129], v[128:129], 1.0 op_sel_hi:[1,0]
	v_pk_add_f32 v[120:121], v[148:149], 1.0 op_sel_hi:[1,0]
	v_pk_add_f32 v[126:127], v[126:127], 1.0 op_sel_hi:[1,0]
	v_rcp_f32_e32 v128, v128
	v_rcp_f32_e32 v129, v129
	v_pk_add_f32 v[118:119], v[118:119], 1.0 op_sel_hi:[1,0]
	v_rcp_f32_e32 v120, v120
	v_rcp_f32_e32 v121, v121
	v_rcp_f32_e32 v126, v126
	v_rcp_f32_e32 v127, v127
	v_rcp_f32_e32 v118, v118
	v_rcp_f32_e32 v119, v119
	v_mul_f32_e32 v144, v144, v144
	v_pk_mul_f32 v[114:115], v[114:115], v[144:145] op_sel_hi:[1,0]
	s_lshl_b32 s14, s35, 7
	v_pk_mul_f32 v[122:123], v[122:123], v[144:145] op_sel_hi:[1,0]
	v_pk_mul_f32 v[124:125], v[124:125], v[144:145] op_sel_hi:[1,0]
	v_pk_mul_f32 v[116:117], v[116:117], v[144:145] op_sel_hi:[1,0]
	v_pk_mul_f32 v[114:115], v[114:115], v[128:129]
	v_lshl_add_u32 v141, s36, 8, v138
	s_ashr_i32 s15, s14, 31
	v_pk_mul_f32 v[120:121], v[122:123], v[120:121]
	v_pk_mul_f32 v[122:123], v[124:125], v[126:127]
	v_pk_mul_f32 v[124:125], v[116:117], v[118:119]
	v_cvt_pk_bf16_f32 v118, v114, v115
	v_mov_b64_e32 v[114:115], s[0:1]
	s_movk_i32 s7, 0x1600
	v_cvt_pk_bf16_f32 v116, v120, v121
	v_mad_i64_i32 v[120:121], s[16:17], v141, s7, v[114:115]
	s_lshl_b64 s[14:15], s[14:15], 1
	v_lshl_add_u64 v[120:121], v[120:121], 0, s[14:15]
	v_lshl_add_u64 v[120:121], v[120:121], 0, s[96:97]
	v_lshl_add_u64 v[120:121], v[120:121], 0, v[190:191]
	v_cvt_pk_bf16_f32 v117, v122, v123
	v_cvt_pk_bf16_f32 v119, v124, v125
	global_store_dwordx4 v[120:121], v[116:119], off
	v_pk_mul_f32 v[108:109], v[112:113], v[108:109]
	v_pk_mul_f32 v[106:107], v[110:111], v[106:107]
	v_mul_f32_e32 v116, 0xbfb8aa3b, v145
	v_pk_mul_f32 v[120:121], v[110:111], v[116:117] op_sel_hi:[1,0]
	v_pk_mul_f32 v[110:111], v[112:113], v[116:117] op_sel_hi:[1,0]
	v_exp_f32_e32 v120, v120
	v_exp_f32_e32 v121, v121
	v_pk_mul_f32 v[112:113], v[102:103], v[116:117] op_sel_hi:[1,0]
	v_pk_mul_f32 v[98:99], v[102:103], v[98:99]
	v_pk_mul_f32 v[102:103], v[104:105], v[116:117] op_sel_hi:[1,0]
	v_exp_f32_e32 v110, v110
	v_exp_f32_e32 v111, v111
	v_exp_f32_e32 v112, v112
	v_exp_f32_e32 v113, v113
	v_exp_f32_e32 v102, v102
	v_exp_f32_e32 v103, v103
	v_pk_mul_f32 v[100:101], v[104:105], v[100:101]
	v_pk_add_f32 v[104:105], v[120:121], 1.0 op_sel_hi:[1,0]
	v_pk_add_f32 v[110:111], v[110:111], 1.0 op_sel_hi:[1,0]
	v_rcp_f32_e32 v104, v104
	v_rcp_f32_e32 v105, v105
	v_pk_add_f32 v[112:113], v[112:113], 1.0 op_sel_hi:[1,0]
	v_pk_add_f32 v[102:103], v[102:103], 1.0 op_sel_hi:[1,0]
	v_rcp_f32_e32 v110, v110
	v_rcp_f32_e32 v111, v111
	v_rcp_f32_e32 v112, v112
	v_rcp_f32_e32 v113, v113
	v_rcp_f32_e32 v102, v102
	v_rcp_f32_e32 v103, v103
	v_mul_f32_e32 v118, v145, v145
	v_pk_mul_f32 v[106:107], v[106:107], v[118:119] op_sel_hi:[1,0]
	v_pk_mul_f32 v[108:109], v[108:109], v[118:119] op_sel_hi:[1,0]
	v_pk_mul_f32 v[98:99], v[98:99], v[118:119] op_sel_hi:[1,0]
	v_pk_mul_f32 v[100:101], v[100:101], v[118:119] op_sel_hi:[1,0]
	v_pk_mul_f32 v[104:105], v[106:107], v[104:105]
	v_pk_mul_f32 v[106:107], v[108:109], v[110:111]
	v_pk_mul_f32 v[108:109], v[98:99], v[112:113]
	v_pk_mul_f32 v[102:103], v[100:101], v[102:103]
	v_or_b32_e32 v110, 16, v141
	v_cvt_pk_bf16_f32 v98, v104, v105
	ds_read2_b32 v[104:105], v142 offset0:32 offset1:48
	v_cvt_pk_bf16_f32 v101, v102, v103
	v_mad_i64_i32 v[102:103], s[16:17], v110, s7, v[114:115]
	v_lshl_add_u64 v[102:103], v[102:103], 0, s[14:15]
	v_lshl_add_u64 v[102:103], v[102:103], 0, s[96:97]
	v_lshl_add_u64 v[102:103], v[102:103], 0, v[190:191]
	v_cvt_pk_bf16_f32 v99, v106, v107
	v_cvt_pk_bf16_f32 v100, v108, v109
	global_store_dwordx4 v[102:103], v[98:101], off
	v_pk_mul_f32 v[92:93], v[96:97], v[92:93]
	v_pk_mul_f32 v[90:91], v[94:95], v[90:91]
	s_waitcnt lgkmcnt(0)
	v_mul_f32_e32 v98, 0xbfb8aa3b, v104
	v_pk_mul_f32 v[102:103], v[94:95], v[98:99] op_sel_hi:[1,0]
	v_pk_mul_f32 v[94:95], v[96:97], v[98:99] op_sel_hi:[1,0]
	v_pk_mul_f32 v[96:97], v[86:87], v[98:99] op_sel_hi:[1,0]
	v_pk_mul_f32 v[82:83], v[86:87], v[82:83]
	v_pk_mul_f32 v[86:87], v[88:89], v[98:99] op_sel_hi:[1,0]
	v_exp_f32_e32 v102, v102
	v_exp_f32_e32 v103, v103
	v_exp_f32_e32 v94, v94
	v_exp_f32_e32 v95, v95
	v_exp_f32_e32 v86, v86
	v_exp_f32_e32 v87, v87
	v_exp_f32_e32 v96, v96
	v_exp_f32_e32 v97, v97
	v_pk_mul_f32 v[84:85], v[88:89], v[84:85]
	v_pk_add_f32 v[88:89], v[102:103], 1.0 op_sel_hi:[1,0]
	v_pk_add_f32 v[94:95], v[94:95], 1.0 op_sel_hi:[1,0]
	v_pk_add_f32 v[86:87], v[86:87], 1.0 op_sel_hi:[1,0]
	v_rcp_f32_e32 v88, v88
	v_rcp_f32_e32 v89, v89
	v_rcp_f32_e32 v94, v94
	v_rcp_f32_e32 v95, v95
	v_rcp_f32_e32 v86, v86
	v_rcp_f32_e32 v87, v87
	v_mul_f32_e32 v100, v104, v104
	v_pk_mul_f32 v[90:91], v[90:91], v[100:101] op_sel_hi:[1,0]
	v_pk_mul_f32 v[92:93], v[92:93], v[100:101] op_sel_hi:[1,0]
	v_pk_mul_f32 v[84:85], v[84:85], v[100:101] op_sel_hi:[1,0]
	v_pk_add_f32 v[96:97], v[96:97], 1.0 op_sel_hi:[1,0]
	v_pk_mul_f32 v[88:89], v[90:91], v[88:89]
	v_rcp_f32_e32 v96, v96
	v_rcp_f32_e32 v97, v97
	v_pk_mul_f32 v[90:91], v[92:93], v[94:95]
	v_pk_mul_f32 v[86:87], v[84:85], v[86:87]
	v_or_b32_e32 v94, 32, v141
	v_cvt_pk_bf16_f32 v85, v86, v87
	v_mad_i64_i32 v[86:87], s[16:17], v94, s7, v[114:115]
	v_lshl_add_u64 v[86:87], v[86:87], 0, s[14:15]
	v_pk_mul_f32 v[82:83], v[82:83], v[100:101] op_sel_hi:[1,0]
	v_lshl_add_u64 v[86:87], v[86:87], 0, s[96:97]
	v_pk_mul_f32 v[92:93], v[82:83], v[96:97]
	v_cvt_pk_bf16_f32 v82, v88, v89
	v_lshl_add_u64 v[86:87], v[86:87], 0, v[190:191]
	v_cvt_pk_bf16_f32 v83, v90, v91
	v_cvt_pk_bf16_f32 v84, v92, v93
	global_store_dwordx4 v[86:87], v[82:85], off
	v_pk_mul_f32 v[76:77], v[80:81], v[76:77]
	v_pk_mul_f32 v[74:75], v[78:79], v[74:75]
	v_mul_f32_e32 v82, 0xbfb8aa3b, v105
	v_pk_mul_f32 v[86:87], v[78:79], v[82:83] op_sel_hi:[1,0]
	v_pk_mul_f32 v[78:79], v[80:81], v[82:83] op_sel_hi:[1,0]
	v_exp_f32_e32 v86, v86
	v_exp_f32_e32 v87, v87
	v_pk_mul_f32 v[80:81], v[70:71], v[82:83] op_sel_hi:[1,0]
	v_pk_mul_f32 v[66:67], v[70:71], v[66:67]
	v_pk_mul_f32 v[70:71], v[72:73], v[82:83] op_sel_hi:[1,0]
	v_exp_f32_e32 v78, v78
	v_exp_f32_e32 v79, v79
	v_exp_f32_e32 v80, v80
	v_exp_f32_e32 v81, v81
	v_exp_f32_e32 v70, v70
	v_exp_f32_e32 v71, v71
	v_pk_mul_f32 v[68:69], v[72:73], v[68:69]
	v_pk_add_f32 v[72:73], v[86:87], 1.0 op_sel_hi:[1,0]
	v_pk_add_f32 v[78:79], v[78:79], 1.0 op_sel_hi:[1,0]
	v_rcp_f32_e32 v72, v72
	v_rcp_f32_e32 v73, v73
	v_pk_add_f32 v[80:81], v[80:81], 1.0 op_sel_hi:[1,0]
	v_pk_add_f32 v[70:71], v[70:71], 1.0 op_sel_hi:[1,0]
	v_rcp_f32_e32 v78, v78
	v_rcp_f32_e32 v79, v79
	v_rcp_f32_e32 v80, v80
	v_rcp_f32_e32 v81, v81
	v_rcp_f32_e32 v70, v70
	v_rcp_f32_e32 v71, v71
	v_mul_f32_e32 v84, v105, v105
	v_pk_mul_f32 v[74:75], v[74:75], v[84:85] op_sel_hi:[1,0]
	v_pk_mul_f32 v[76:77], v[76:77], v[84:85] op_sel_hi:[1,0]
	v_pk_mul_f32 v[66:67], v[66:67], v[84:85] op_sel_hi:[1,0]
	v_pk_mul_f32 v[68:69], v[68:69], v[84:85] op_sel_hi:[1,0]
	v_pk_mul_f32 v[72:73], v[74:75], v[72:73]
	v_pk_mul_f32 v[74:75], v[76:77], v[78:79]
	v_pk_mul_f32 v[76:77], v[66:67], v[80:81]
	v_pk_mul_f32 v[70:71], v[68:69], v[70:71]
	v_or_b32_e32 v78, 48, v141
	v_cvt_pk_bf16_f32 v66, v72, v73
	ds_read2_b32 v[72:73], v142 offset0:128 offset1:144
	v_cvt_pk_bf16_f32 v69, v70, v71
	v_mad_i64_i32 v[70:71], s[16:17], v78, s7, v[114:115]
	v_lshl_add_u64 v[70:71], v[70:71], 0, s[14:15]
	v_lshl_add_u64 v[70:71], v[70:71], 0, s[96:97]
	v_cvt_pk_bf16_f32 v67, v74, v75
	v_lshl_add_u64 v[70:71], v[70:71], 0, v[190:191]
	v_cvt_pk_bf16_f32 v68, v76, v77
	global_store_dwordx4 v[70:71], v[66:69], off
	v_pk_mul_f32 v[60:61], v[64:65], v[60:61]
	v_pk_mul_f32 v[58:59], v[62:63], v[58:59]
	v_add_u32_e32 v67, 0x80, v141
	s_waitcnt lgkmcnt(0)
	v_mul_f32_e32 v66, 0xbfb8aa3b, v72
	v_pk_mul_f32 v[70:71], v[62:63], v[66:67] op_sel_hi:[1,0]
	v_pk_mul_f32 v[62:63], v[64:65], v[66:67] op_sel_hi:[1,0]
	v_pk_mul_f32 v[64:65], v[54:55], v[66:67] op_sel_hi:[1,0]
	v_pk_mul_f32 v[50:51], v[54:55], v[50:51]
	v_pk_mul_f32 v[54:55], v[56:57], v[66:67] op_sel_hi:[1,0]
	v_exp_f32_e32 v70, v70
	v_exp_f32_e32 v54, v54
	v_exp_f32_e32 v55, v55
	v_exp_f32_e32 v71, v71
	v_exp_f32_e32 v62, v62
	v_exp_f32_e32 v63, v63
	v_exp_f32_e32 v64, v64
	v_exp_f32_e32 v65, v65
	v_pk_add_f32 v[54:55], v[54:55], 1.0 op_sel_hi:[1,0]
	v_mul_f32_e32 v68, v72, v72
	v_rcp_f32_e32 v54, v54
	v_rcp_f32_e32 v55, v55
	v_pk_mul_f32 v[52:53], v[56:57], v[52:53]
	v_pk_add_f32 v[56:57], v[70:71], 1.0 op_sel_hi:[1,0]
	v_pk_mul_f32 v[52:53], v[52:53], v[68:69] op_sel_hi:[1,0]
	v_pk_add_f32 v[62:63], v[62:63], 1.0 op_sel_hi:[1,0]
	v_pk_add_f32 v[64:65], v[64:65], 1.0 op_sel_hi:[1,0]
	v_rcp_f32_e32 v56, v56
	v_rcp_f32_e32 v57, v57
	v_rcp_f32_e32 v62, v62
	v_rcp_f32_e32 v63, v63
	v_rcp_f32_e32 v64, v64
	v_rcp_f32_e32 v65, v65
	v_pk_mul_f32 v[54:55], v[52:53], v[54:55]
	v_pk_mul_f32 v[58:59], v[58:59], v[68:69] op_sel_hi:[1,0]
	v_cvt_pk_bf16_f32 v53, v54, v55
	v_mad_i64_i32 v[54:55], s[16:17], v67, s7, v[114:115]
	v_lshl_add_u64 v[54:55], v[54:55], 0, s[14:15]
	v_pk_mul_f32 v[60:61], v[60:61], v[68:69] op_sel_hi:[1,0]
	v_pk_mul_f32 v[50:51], v[50:51], v[68:69] op_sel_hi:[1,0]
	v_lshl_add_u64 v[54:55], v[54:55], 0, s[96:97]
	v_pk_mul_f32 v[56:57], v[58:59], v[56:57]
	v_pk_mul_f32 v[58:59], v[60:61], v[62:63]
	v_pk_mul_f32 v[60:61], v[50:51], v[64:65]
	v_cvt_pk_bf16_f32 v50, v56, v57
	v_lshl_add_u64 v[54:55], v[54:55], 0, v[190:191]
	v_cvt_pk_bf16_f32 v51, v58, v59
	v_cvt_pk_bf16_f32 v52, v60, v61
	global_store_dwordx4 v[54:55], v[50:53], off
	v_pk_mul_f32 v[44:45], v[48:49], v[44:45]
	v_pk_mul_f32 v[42:43], v[46:47], v[42:43]
	v_mul_f32_e32 v50, 0xbfb8aa3b, v73
	v_pk_mul_f32 v[54:55], v[46:47], v[50:51] op_sel_hi:[1,0]
	v_pk_mul_f32 v[46:47], v[48:49], v[50:51] op_sel_hi:[1,0]
	v_exp_f32_e32 v54, v54
	v_exp_f32_e32 v55, v55
	v_pk_mul_f32 v[48:49], v[38:39], v[50:51] op_sel_hi:[1,0]
	v_pk_mul_f32 v[34:35], v[38:39], v[34:35]
	v_pk_mul_f32 v[38:39], v[40:41], v[50:51] op_sel_hi:[1,0]
	v_exp_f32_e32 v46, v46
	v_exp_f32_e32 v47, v47
	v_exp_f32_e32 v48, v48
	v_exp_f32_e32 v49, v49
	v_exp_f32_e32 v38, v38
	v_exp_f32_e32 v39, v39
	v_pk_mul_f32 v[36:37], v[40:41], v[36:37]
	v_pk_add_f32 v[40:41], v[54:55], 1.0 op_sel_hi:[1,0]
	v_pk_add_f32 v[46:47], v[46:47], 1.0 op_sel_hi:[1,0]
	v_rcp_f32_e32 v40, v40
	v_rcp_f32_e32 v41, v41
	v_pk_add_f32 v[48:49], v[48:49], 1.0 op_sel_hi:[1,0]
	v_pk_add_f32 v[38:39], v[38:39], 1.0 op_sel_hi:[1,0]
	v_rcp_f32_e32 v46, v46
	v_rcp_f32_e32 v47, v47
	v_rcp_f32_e32 v48, v48
	v_rcp_f32_e32 v49, v49
	v_rcp_f32_e32 v38, v38
	v_rcp_f32_e32 v39, v39
	v_mul_f32_e32 v52, v73, v73
	v_pk_mul_f32 v[42:43], v[42:43], v[52:53] op_sel_hi:[1,0]
	v_pk_mul_f32 v[44:45], v[44:45], v[52:53] op_sel_hi:[1,0]
	v_pk_mul_f32 v[34:35], v[34:35], v[52:53] op_sel_hi:[1,0]
	v_pk_mul_f32 v[36:37], v[36:37], v[52:53] op_sel_hi:[1,0]
	v_pk_mul_f32 v[40:41], v[42:43], v[40:41]
	v_pk_mul_f32 v[42:43], v[44:45], v[46:47]
	v_pk_mul_f32 v[44:45], v[34:35], v[48:49]
	v_pk_mul_f32 v[38:39], v[36:37], v[38:39]
	v_add_u32_e32 v46, 0x90, v141
	v_cvt_pk_bf16_f32 v34, v40, v41
	ds_read2_b32 v[40:41], v142 offset0:160 offset1:176
	v_cvt_pk_bf16_f32 v37, v38, v39
	v_mad_i64_i32 v[38:39], s[16:17], v46, s7, v[114:115]
	v_lshl_add_u64 v[38:39], v[38:39], 0, s[14:15]
	v_lshl_add_u64 v[38:39], v[38:39], 0, s[96:97]
	v_lshl_add_u64 v[38:39], v[38:39], 0, v[190:191]
	v_cvt_pk_bf16_f32 v35, v42, v43
	v_cvt_pk_bf16_f32 v36, v44, v45
	global_store_dwordx4 v[38:39], v[34:37], off
	v_pk_mul_f32 v[28:29], v[32:33], v[28:29]
	v_pk_mul_f32 v[26:27], v[30:31], v[26:27]
	s_waitcnt lgkmcnt(0)
	v_mul_f32_e32 v34, 0xbfb8aa3b, v40
	v_pk_mul_f32 v[38:39], v[30:31], v[34:35] op_sel_hi:[1,0]
	v_pk_mul_f32 v[30:31], v[32:33], v[34:35] op_sel_hi:[1,0]
	v_pk_mul_f32 v[32:33], v[22:23], v[34:35] op_sel_hi:[1,0]
	v_pk_mul_f32 v[18:19], v[22:23], v[18:19]
	v_pk_mul_f32 v[22:23], v[24:25], v[34:35] op_sel_hi:[1,0]
	v_exp_f32_e32 v38, v38
	v_exp_f32_e32 v39, v39
	v_exp_f32_e32 v30, v30
	v_exp_f32_e32 v31, v31
	v_exp_f32_e32 v22, v22
	v_exp_f32_e32 v23, v23
	v_exp_f32_e32 v32, v32
	v_exp_f32_e32 v33, v33
	v_pk_mul_f32 v[20:21], v[24:25], v[20:21]
	v_pk_add_f32 v[24:25], v[38:39], 1.0 op_sel_hi:[1,0]
	v_pk_add_f32 v[30:31], v[30:31], 1.0 op_sel_hi:[1,0]
	v_pk_add_f32 v[22:23], v[22:23], 1.0 op_sel_hi:[1,0]
	v_rcp_f32_e32 v24, v24
	v_rcp_f32_e32 v25, v25
	v_rcp_f32_e32 v30, v30
	v_rcp_f32_e32 v31, v31
	v_rcp_f32_e32 v22, v22
	v_rcp_f32_e32 v23, v23
	v_mul_f32_e32 v36, v40, v40
	v_pk_mul_f32 v[26:27], v[26:27], v[36:37] op_sel_hi:[1,0]
	v_pk_mul_f32 v[28:29], v[28:29], v[36:37] op_sel_hi:[1,0]
	v_pk_mul_f32 v[20:21], v[20:21], v[36:37] op_sel_hi:[1,0]
	v_pk_add_f32 v[32:33], v[32:33], 1.0 op_sel_hi:[1,0]
	v_pk_mul_f32 v[24:25], v[26:27], v[24:25]
	v_rcp_f32_e32 v32, v32
	v_rcp_f32_e32 v33, v33
	v_pk_mul_f32 v[26:27], v[28:29], v[30:31]
	v_pk_mul_f32 v[22:23], v[20:21], v[22:23]
	v_add_u32_e32 v30, 0xa0, v141
	v_cvt_pk_bf16_f32 v21, v22, v23
	v_mad_i64_i32 v[22:23], s[16:17], v30, s7, v[114:115]
	v_lshl_add_u64 v[22:23], v[22:23], 0, s[14:15]
	v_pk_mul_f32 v[18:19], v[18:19], v[36:37] op_sel_hi:[1,0]
	v_lshl_add_u64 v[22:23], v[22:23], 0, s[96:97]
	v_pk_mul_f32 v[28:29], v[18:19], v[32:33]
	v_cvt_pk_bf16_f32 v18, v24, v25
	v_lshl_add_u64 v[22:23], v[22:23], 0, v[190:191]
	v_cvt_pk_bf16_f32 v19, v26, v27
	v_cvt_pk_bf16_f32 v20, v28, v29
	global_store_dwordx4 v[22:23], v[18:21], off
	v_pk_mul_f32 v[12:13], v[16:17], v[12:13]
	v_pk_mul_f32 v[10:11], v[14:15], v[10:11]
	v_mul_f32_e32 v18, 0xbfb8aa3b, v41
	v_pk_mul_f32 v[22:23], v[14:15], v[18:19] op_sel_hi:[1,0]
	v_pk_mul_f32 v[14:15], v[16:17], v[18:19] op_sel_hi:[1,0]
	v_pk_mul_f32 v[16:17], v[6:7], v[18:19] op_sel_hi:[1,0]
	v_pk_mul_f32 v[2:3], v[6:7], v[2:3]
	v_pk_mul_f32 v[6:7], v[8:9], v[18:19] op_sel_hi:[1,0]
	v_exp_f32_e32 v22, v22
	v_exp_f32_e32 v23, v23
	v_exp_f32_e32 v14, v14
	v_exp_f32_e32 v15, v15
	v_exp_f32_e32 v6, v6
	v_exp_f32_e32 v7, v7
	v_pk_mul_f32 v[4:5], v[8:9], v[4:5]
	v_pk_add_f32 v[8:9], v[22:23], 1.0 op_sel_hi:[1,0]
	v_pk_add_f32 v[14:15], v[14:15], 1.0 op_sel_hi:[1,0]
	v_pk_add_f32 v[6:7], v[6:7], 1.0 op_sel_hi:[1,0]
	v_exp_f32_e32 v16, v16
	v_exp_f32_e32 v17, v17
	v_rcp_f32_e32 v8, v8
	v_rcp_f32_e32 v9, v9
	v_rcp_f32_e32 v14, v14
	v_rcp_f32_e32 v15, v15
	v_rcp_f32_e32 v6, v6
	v_rcp_f32_e32 v7, v7
	v_mul_f32_e32 v20, v41, v41
	v_pk_mul_f32 v[10:11], v[10:11], v[20:21] op_sel_hi:[1,0]
	v_pk_mul_f32 v[12:13], v[12:13], v[20:21] op_sel_hi:[1,0]
	v_pk_mul_f32 v[4:5], v[4:5], v[20:21] op_sel_hi:[1,0]
	v_pk_add_f32 v[16:17], v[16:17], 1.0 op_sel_hi:[1,0]
	v_pk_mul_f32 v[8:9], v[10:11], v[8:9]
	v_pk_mul_f32 v[10:11], v[12:13], v[14:15]
	v_pk_mul_f32 v[6:7], v[4:5], v[6:7]
	v_add_u32_e32 v14, 0xb0, v141
	v_rcp_f32_e32 v16, v16
	v_rcp_f32_e32 v17, v17
	v_cvt_pk_bf16_f32 v5, v6, v7
	v_mad_i64_i32 v[6:7], s[16:17], v14, s7, v[114:115]
	v_lshl_add_u64 v[6:7], v[6:7], 0, s[14:15]
	v_lshl_add_u64 v[6:7], v[6:7], 0, s[96:97]
	v_pk_mul_f32 v[2:3], v[2:3], v[20:21] op_sel_hi:[1,0]
	v_lshl_add_u64 v[6:7], v[6:7], 0, v[190:191]
	s_and_b64 vcc, exec, s[38:39]
	s_mov_b32 s35, s6
	s_mov_b32 s36, s8
	s_mov_b64 s[16:17], s[12:13]
	s_mov_b64 s[14:15], s[10:11]
	s_mov_b32 s37, s34
	v_pk_mul_f32 v[12:13], v[2:3], v[16:17]
	v_cvt_pk_bf16_f32 v2, v8, v9
	v_cvt_pk_bf16_f32 v3, v10, v11
	s_nop 0
	v_cvt_pk_bf16_f32 v4, v12, v13
	global_store_dwordx4 v[6:7], v[2:5], off
	s_cbranch_vccz .LBB0_92
	s_waitcnt vmcnt(0)
	v_readlane_b32 s30, v252, 21
	s_cmpk_gt_u32 s22, 0xff
	v_readlane_b32 s31, v252, 22
	s_mov_b32 s34, 0x800000
	s_movk_i32 s35, 0x4000
	s_movk_i32 s36, 0x90
	s_movk_i32 s37, 0x300
	s_movk_i32 s54, 0x2810
	s_movk_i32 s55, 0xdff
	v_readlane_b32 s56, v252, 31
	s_movk_i32 s57, 0x110
	s_mov_b32 s58, 0x2aaaaaab
	s_movk_i32 s59, 0xffd0
	v_readlane_b32 s76, v252, 46
	s_cbranch_scc1 .LBB0_103
	s_barrier

.LBB0_1155:
	v_mov_b64_e32 v[2:3], 0x294
	s_ashr_i32 s5, s4, 31
	v_cmp_lt_i64_e32 vcc, s[10:11], v[2:3]
	s_lshl_b64 s[10:11], s[4:5], 19
	s_add_u32 s10, s46, s10
	s_addc_u32 s11, s47, s11
	s_and_b64 s[12:13], vcc, exec
	s_cselect_b32 s5, s11, s15
	s_cselect_b32 s34, s10, s14
	s_ashr_i32 s3, s2, 31
	s_lshl_b64 s[12:13], s[2:3], 19
	s_add_u32 s12, s23, s12
	s_addc_u32 s13, s24, s13
	s_and_b64 s[18:19], vcc, exec
	s_cselect_b32 s3, s13, s17
	s_cselect_b32 s35, s12, s16
	s_add_u32 s14, s14, 0x40080
	s_addc_u32 s15, s15, 0
	s_add_u32 s36, s16, 0x100
	s_addc_u32 s37, s17, 0
	s_mov_b32 s40, -2
	s_add_u32 s16, s14, 0xfffc0080
	s_addc_u32 s17, s15, -1
	s_add_i32 s41, 0, 0x10000
	v_add_u32_e32 v249, s41, v154
	ds_read_b128 v[146:149], v249
	ds_read_b128 v[150:153], v249 offset:1024
	ds_read_b128 v[164:167], v249 offset:2048
	ds_read_b128 v[168:171], v249 offset:3072
	s_cmp_eq_u32 s40, 12
	s_cselect_b32 s19, s5, s17
	s_cselect_b32 s18, s34, s16
	s_cselect_b32 s17, s3, s37
	s_cselect_b32 s16, s35, s36
	s_add_i32 s44, 0, 0x14000
	ds_read_b128 v[220:223], v249 offset:16384
	ds_read_b128 v[224:227], v249 offset:17408
	ds_read_b128 v[228:231], v249 offset:18432
	ds_read_b128 v[232:235], v249 offset:19456
	s_add_i32 m0, s9, 0xc000
	ds_read_b128 v[172:175], v163
	ds_read_b128 v[176:179], v163 offset:1024
	ds_read_b128 v[180:183], v163 offset:2048
	ds_read_b128 v[184:187], v163 offset:3072
	ds_read_b128 v[204:207], v163 offset:4096
	ds_read_b128 v[208:211], v163 offset:5120
	ds_read_b128 v[212:215], v163 offset:6144
	ds_read_b128 v[216:219], v163 offset:7168
	global_load_lds_dwordx4 v138, s[14:15]
	s_add_i32 m0, s9, 0xe000
	s_nop 0
	global_load_lds_dwordx4 v140, s[14:15]
	s_waitcnt vmcnt(8) lgkmcnt(0)
	s_barrier
	s_setprio 1
	v_mfma_f32_16x16x32_bf16 v[126:129], v[146:149], v[172:175], 0
	v_mfma_f32_16x16x32_bf16 v[122:125], v[164:167], v[172:175], 0
	v_mfma_f32_16x16x32_bf16 v[114:117], v[146:149], v[180:183], 0
	v_mfma_f32_16x16x32_bf16 v[106:109], v[164:167], v[180:183], 0
	v_mfma_f32_16x16x32_bf16 v[98:101], v[146:149], v[204:207], 0
	v_mfma_f32_16x16x32_bf16 v[90:93], v[164:167], v[204:207], 0
	v_mfma_f32_16x16x32_bf16 v[82:85], v[146:149], v[212:215], 0
	v_mfma_f32_16x16x32_bf16 v[74:77], v[164:167], v[212:215], 0
	v_mfma_f32_16x16x32_bf16 v[126:129], v[150:153], v[176:179], v[126:129]
	v_mfma_f32_16x16x32_bf16 v[122:125], v[168:171], v[176:179], v[122:125]
	v_mfma_f32_16x16x32_bf16 v[114:117], v[150:153], v[184:187], v[114:117]
	v_mfma_f32_16x16x32_bf16 v[106:109], v[168:171], v[184:187], v[106:109]
	v_mfma_f32_16x16x32_bf16 v[98:101], v[150:153], v[208:211], v[98:101]
	v_mfma_f32_16x16x32_bf16 v[90:93], v[168:171], v[208:211], v[90:93]
	v_mfma_f32_16x16x32_bf16 v[82:85], v[150:153], v[216:219], v[82:85]
	v_mfma_f32_16x16x32_bf16 v[74:77], v[168:171], v[216:219], v[74:77]
	v_mfma_f32_16x16x32_bf16 v[118:121], v[220:223], v[172:175], 0
	v_mfma_f32_16x16x32_bf16 v[110:113], v[228:231], v[172:175], 0
	v_mfma_f32_16x16x32_bf16 v[102:105], v[220:223], v[180:183], 0
	v_mfma_f32_16x16x32_bf16 v[94:97], v[228:231], v[180:183], 0
	v_mfma_f32_16x16x32_bf16 v[86:89], v[220:223], v[204:207], 0
	v_mfma_f32_16x16x32_bf16 v[78:81], v[228:231], v[204:207], 0
	v_mfma_f32_16x16x32_bf16 v[70:73], v[220:223], v[212:215], 0
	v_mfma_f32_16x16x32_bf16 v[66:69], v[228:231], v[212:215], 0
	v_mfma_f32_16x16x32_bf16 v[118:121], v[224:227], v[176:179], v[118:121]
	v_mfma_f32_16x16x32_bf16 v[110:113], v[232:235], v[176:179], v[110:113]
	v_mfma_f32_16x16x32_bf16 v[102:105], v[224:227], v[184:187], v[102:105]
	v_mfma_f32_16x16x32_bf16 v[94:97], v[232:235], v[184:187], v[94:97]
	v_mfma_f32_16x16x32_bf16 v[86:89], v[224:227], v[208:211], v[86:89]
	v_mfma_f32_16x16x32_bf16 v[78:81], v[232:235], v[208:211], v[78:81]
	v_mfma_f32_16x16x32_bf16 v[70:73], v[224:227], v[216:219], v[70:73]
	v_mfma_f32_16x16x32_bf16 v[66:69], v[232:235], v[216:219], v[66:69]
	s_setprio 0
	s_barrier
	ds_read_b128 v[172:175], v163 offset:16384
	ds_read_b128 v[176:179], v163 offset:17408
	ds_read_b128 v[180:183], v163 offset:18432
	ds_read_b128 v[184:187], v163 offset:19456
	ds_read_b128 v[204:207], v163 offset:20480
	ds_read_b128 v[208:211], v163 offset:21504
	ds_read_b128 v[212:215], v163 offset:22528
	ds_read_b128 v[216:219], v163 offset:23552
	s_add_i32 s41, s41, s25
	s_mov_b32 m0, s41
	s_nop 0
	global_load_lds_dwordx4 v132, s[16:17]
	s_add_i32 m0, s41, 0x2000
	s_nop 0
	global_load_lds_dwordx4 v136, s[16:17]
	s_mov_b32 m0, s9
	s_add_u32 s98, s18, 0x80
	s_addc_u32 s99, s19, 0
	global_load_lds_dwordx4 v130, s[18:19]
	s_mov_b32 m0, s26
	s_nop 0
	global_load_lds_dwordx4 v134, s[18:19]
	s_add_u32 s42, s16, 0x40000
	s_addc_u32 s43, s17, 0
	s_add_i32 s41, s44, s25
	s_mov_b32 m0, s41
	s_nop 0
	global_load_lds_dwordx4 v132, s[42:43]
	s_add_i32 m0, s41, 0x2000
	s_nop 0
	global_load_lds_dwordx4 v136, s[42:43]
	s_waitcnt vmcnt(8) lgkmcnt(0)
	s_barrier
	s_setprio 1
	v_mfma_f32_16x16x32_bf16 v[62:65], v[146:149], v[172:175], 0
	v_mfma_f32_16x16x32_bf16 v[58:61], v[164:167], v[172:175], 0
	v_mfma_f32_16x16x32_bf16 v[50:53], v[146:149], v[180:183], 0
	v_mfma_f32_16x16x32_bf16 v[42:45], v[164:167], v[180:183], 0
	v_mfma_f32_16x16x32_bf16 v[34:37], v[146:149], v[204:207], 0
	v_mfma_f32_16x16x32_bf16 v[26:29], v[164:167], v[204:207], 0
	v_mfma_f32_16x16x32_bf16 v[18:21], v[146:149], v[212:215], 0
	v_mfma_f32_16x16x32_bf16 v[10:13], v[164:167], v[212:215], 0
	v_mfma_f32_16x16x32_bf16 v[62:65], v[150:153], v[176:179], v[62:65]
	v_mfma_f32_16x16x32_bf16 v[58:61], v[168:171], v[176:179], v[58:61]
	v_mfma_f32_16x16x32_bf16 v[50:53], v[150:153], v[184:187], v[50:53]
	v_mfma_f32_16x16x32_bf16 v[42:45], v[168:171], v[184:187], v[42:45]
	v_mfma_f32_16x16x32_bf16 v[34:37], v[150:153], v[208:211], v[34:37]
	v_mfma_f32_16x16x32_bf16 v[26:29], v[168:171], v[208:211], v[26:29]
	v_mfma_f32_16x16x32_bf16 v[18:21], v[150:153], v[216:219], v[18:21]
	v_mfma_f32_16x16x32_bf16 v[10:13], v[168:171], v[216:219], v[10:13]
	v_mfma_f32_16x16x32_bf16 v[54:57], v[220:223], v[172:175], 0
	v_mfma_f32_16x16x32_bf16 v[46:49], v[228:231], v[172:175], 0
	v_mfma_f32_16x16x32_bf16 v[38:41], v[220:223], v[180:183], 0
	v_mfma_f32_16x16x32_bf16 v[30:33], v[228:231], v[180:183], 0
	v_mfma_f32_16x16x32_bf16 v[22:25], v[220:223], v[204:207], 0
	v_mfma_f32_16x16x32_bf16 v[14:17], v[228:231], v[204:207], 0
	v_mfma_f32_16x16x32_bf16 v[6:9], v[220:223], v[212:215], 0
	v_mfma_f32_16x16x32_bf16 v[2:5], v[228:231], v[212:215], 0
	v_mfma_f32_16x16x32_bf16 v[54:57], v[224:227], v[176:179], v[54:57]
	v_mfma_f32_16x16x32_bf16 v[46:49], v[232:235], v[176:179], v[46:49]
	v_mfma_f32_16x16x32_bf16 v[38:41], v[224:227], v[184:187], v[38:41]
	v_mfma_f32_16x16x32_bf16 v[30:33], v[232:235], v[184:187], v[30:33]
	v_mfma_f32_16x16x32_bf16 v[22:25], v[224:227], v[208:211], v[22:25]
	v_mfma_f32_16x16x32_bf16 v[14:17], v[232:235], v[208:211], v[14:17]
	v_mfma_f32_16x16x32_bf16 v[6:9], v[224:227], v[216:219], v[6:9]
	v_mfma_f32_16x16x32_bf16 v[2:5], v[232:235], v[216:219], v[2:5]
	s_setprio 0
	s_barrier
	s_add_i32 s41, 0, 0x18000
	ds_read_b128 v[146:149], v249 offset:32768
	ds_read_b128 v[150:153], v249 offset:33792
	ds_read_b128 v[164:167], v249 offset:34816
	ds_read_b128 v[168:171], v249 offset:35840
	s_add_u32 s18, s18, 0x40000
	s_addc_u32 s19, s19, 0
	s_mov_b32 m0, s27
	ds_read_b128 v[172:175], v163 offset:32768
	ds_read_b128 v[176:179], v163 offset:33792
	ds_read_b128 v[180:183], v163 offset:34816
	ds_read_b128 v[184:187], v163 offset:35840
	ds_read_b128 v[204:207], v163 offset:36864
	ds_read_b128 v[208:211], v163 offset:37888
	ds_read_b128 v[212:215], v163 offset:38912
	ds_read_b128 v[216:219], v163 offset:39936
	global_load_lds_dwordx4 v130, s[18:19]
	s_mov_b32 m0, s28
	s_nop 0
	global_load_lds_dwordx4 v134, s[18:19]
	s_add_i32 s18, 0, 0x1c000
	ds_read_b128 v[220:223], v249 offset:49152
	ds_read_b128 v[224:227], v249 offset:50176
	ds_read_b128 v[228:231], v249 offset:51200
	ds_read_b128 v[232:235], v249 offset:52224
	s_waitcnt vmcnt(8) lgkmcnt(0)
	s_barrier
	s_setprio 1
	v_mfma_f32_16x16x32_bf16 v[126:129], v[146:149], v[172:175], v[126:129]
	v_mfma_f32_16x16x32_bf16 v[122:125], v[164:167], v[172:175], v[122:125]
	v_mfma_f32_16x16x32_bf16 v[114:117], v[146:149], v[180:183], v[114:117]
	v_mfma_f32_16x16x32_bf16 v[106:109], v[164:167], v[180:183], v[106:109]
	v_mfma_f32_16x16x32_bf16 v[98:101], v[146:149], v[204:207], v[98:101]
	v_mfma_f32_16x16x32_bf16 v[90:93], v[164:167], v[204:207], v[90:93]
	v_mfma_f32_16x16x32_bf16 v[82:85], v[146:149], v[212:215], v[82:85]
	v_mfma_f32_16x16x32_bf16 v[74:77], v[164:167], v[212:215], v[74:77]
	v_mfma_f32_16x16x32_bf16 v[126:129], v[150:153], v[176:179], v[126:129]
	v_mfma_f32_16x16x32_bf16 v[122:125], v[168:171], v[176:179], v[122:125]
	v_mfma_f32_16x16x32_bf16 v[114:117], v[150:153], v[184:187], v[114:117]
	v_mfma_f32_16x16x32_bf16 v[106:109], v[168:171], v[184:187], v[106:109]
	v_mfma_f32_16x16x32_bf16 v[98:101], v[150:153], v[208:211], v[98:101]
	v_mfma_f32_16x16x32_bf16 v[90:93], v[168:171], v[208:211], v[90:93]
	v_mfma_f32_16x16x32_bf16 v[82:85], v[150:153], v[216:219], v[82:85]
	v_mfma_f32_16x16x32_bf16 v[74:77], v[168:171], v[216:219], v[74:77]
	v_mfma_f32_16x16x32_bf16 v[118:121], v[220:223], v[172:175], v[118:121]
	v_mfma_f32_16x16x32_bf16 v[110:113], v[228:231], v[172:175], v[110:113]
	v_mfma_f32_16x16x32_bf16 v[102:105], v[220:223], v[180:183], v[102:105]
	v_mfma_f32_16x16x32_bf16 v[94:97], v[228:231], v[180:183], v[94:97]
	v_mfma_f32_16x16x32_bf16 v[86:89], v[220:223], v[204:207], v[86:89]
	v_mfma_f32_16x16x32_bf16 v[78:81], v[228:231], v[204:207], v[78:81]
	v_mfma_f32_16x16x32_bf16 v[70:73], v[220:223], v[212:215], v[70:73]
	v_mfma_f32_16x16x32_bf16 v[66:69], v[228:231], v[212:215], v[66:69]
	v_mfma_f32_16x16x32_bf16 v[118:121], v[224:227], v[176:179], v[118:121]
	v_mfma_f32_16x16x32_bf16 v[110:113], v[232:235], v[176:179], v[110:113]
	v_mfma_f32_16x16x32_bf16 v[102:105], v[224:227], v[184:187], v[102:105]
	v_mfma_f32_16x16x32_bf16 v[94:97], v[232:235], v[184:187], v[94:97]
	v_mfma_f32_16x16x32_bf16 v[86:89], v[224:227], v[208:211], v[86:89]
	v_mfma_f32_16x16x32_bf16 v[78:81], v[232:235], v[208:211], v[78:81]
	v_mfma_f32_16x16x32_bf16 v[70:73], v[224:227], v[216:219], v[70:73]
	v_mfma_f32_16x16x32_bf16 v[66:69], v[232:235], v[216:219], v[66:69]
	s_setprio 0
	s_barrier
	ds_read_b128 v[172:175], v163 offset:49152
	ds_read_b128 v[176:179], v163 offset:50176
	ds_read_b128 v[180:183], v163 offset:51200
	ds_read_b128 v[184:187], v163 offset:52224
	ds_read_b128 v[204:207], v163 offset:53248
	ds_read_b128 v[208:211], v163 offset:54272
	ds_read_b128 v[212:215], v163 offset:55296
	ds_read_b128 v[216:219], v163 offset:56320
	s_add_i32 s19, s41, s25
	s_mov_b32 m0, s19
	s_add_u32 vcc_lo, s16, 0x80
	s_addc_u32 vcc_hi, s17, 0
	global_load_lds_dwordx4 v132, vcc
	s_add_i32 m0, s19, 0x2000
	s_nop 0
	global_load_lds_dwordx4 v136, vcc
	s_mov_b32 m0, s29
	s_nop 0
	global_load_lds_dwordx4 v130, s[98:99]
	s_mov_b32 m0, s30
	s_nop 0
	global_load_lds_dwordx4 v134, s[98:99]
	s_add_u32 s16, s16, 0x40080
	s_addc_u32 s17, s17, 0
	s_add_i32 s18, s18, s25
	s_mov_b32 m0, s18
	s_nop 0
	global_load_lds_dwordx4 v132, s[16:17]
	s_add_i32 m0, s18, 0x2000
	s_nop 0
	global_load_lds_dwordx4 v136, s[16:17]
	s_add_i32 s40, s40, 2
	s_add_u32 s14, s14, 0x100
	s_addc_u32 s15, s15, 0
	s_add_u32 s36, s36, 0x100
	s_addc_u32 s37, s37, 0
	s_cmp_gt_u32 s40, 13
	s_waitcnt vmcnt(8) lgkmcnt(0)
	s_barrier
	s_setprio 1
	v_mfma_f32_16x16x32_bf16 v[62:65], v[146:149], v[172:175], v[62:65]
	v_mfma_f32_16x16x32_bf16 v[58:61], v[164:167], v[172:175], v[58:61]
	v_mfma_f32_16x16x32_bf16 v[50:53], v[146:149], v[180:183], v[50:53]
	v_mfma_f32_16x16x32_bf16 v[42:45], v[164:167], v[180:183], v[42:45]
	v_mfma_f32_16x16x32_bf16 v[34:37], v[146:149], v[204:207], v[34:37]
	v_mfma_f32_16x16x32_bf16 v[26:29], v[164:167], v[204:207], v[26:29]
	v_mfma_f32_16x16x32_bf16 v[18:21], v[146:149], v[212:215], v[18:21]
	v_mfma_f32_16x16x32_bf16 v[10:13], v[164:167], v[212:215], v[10:13]
	v_mfma_f32_16x16x32_bf16 v[62:65], v[150:153], v[176:179], v[62:65]
	v_mfma_f32_16x16x32_bf16 v[58:61], v[168:171], v[176:179], v[58:61]
	v_mfma_f32_16x16x32_bf16 v[50:53], v[150:153], v[184:187], v[50:53]
	v_mfma_f32_16x16x32_bf16 v[42:45], v[168:171], v[184:187], v[42:45]
	v_mfma_f32_16x16x32_bf16 v[34:37], v[150:153], v[208:211], v[34:37]
	v_mfma_f32_16x16x32_bf16 v[26:29], v[168:171], v[208:211], v[26:29]
	v_mfma_f32_16x16x32_bf16 v[18:21], v[150:153], v[216:219], v[18:21]
	v_mfma_f32_16x16x32_bf16 v[10:13], v[168:171], v[216:219], v[10:13]
	v_mfma_f32_16x16x32_bf16 v[54:57], v[220:223], v[172:175], v[54:57]
	v_mfma_f32_16x16x32_bf16 v[46:49], v[228:231], v[172:175], v[46:49]
	v_mfma_f32_16x16x32_bf16 v[38:41], v[220:223], v[180:183], v[38:41]
	v_mfma_f32_16x16x32_bf16 v[30:33], v[228:231], v[180:183], v[30:33]
	v_mfma_f32_16x16x32_bf16 v[22:25], v[220:223], v[204:207], v[22:25]
	v_mfma_f32_16x16x32_bf16 v[14:17], v[228:231], v[204:207], v[14:17]
	v_mfma_f32_16x16x32_bf16 v[6:9], v[220:223], v[212:215], v[6:9]
	v_mfma_f32_16x16x32_bf16 v[2:5], v[228:231], v[212:215], v[2:5]
	v_mfma_f32_16x16x32_bf16 v[54:57], v[224:227], v[176:179], v[54:57]
	v_mfma_f32_16x16x32_bf16 v[46:49], v[232:235], v[176:179], v[46:49]
	v_mfma_f32_16x16x32_bf16 v[38:41], v[224:227], v[184:187], v[38:41]
	v_mfma_f32_16x16x32_bf16 v[30:33], v[232:235], v[184:187], v[30:33]
	v_mfma_f32_16x16x32_bf16 v[22:25], v[224:227], v[208:211], v[22:25]
	v_mfma_f32_16x16x32_bf16 v[14:17], v[232:235], v[208:211], v[14:17]
	v_mfma_f32_16x16x32_bf16 v[6:9], v[224:227], v[216:219], v[6:9]
	v_mfma_f32_16x16x32_bf16 v[2:5], v[232:235], v[216:219], v[2:5]
	s_setprio 0
	s_barrier
.LBB0_1156:
	s_add_u32 s16, s14, 0xfffc0080
	s_addc_u32 s17, s15, -1
	s_add_i32 s41, 0, 0x10000
	v_add_u32_e32 v249, s41, v154
	ds_read_b128 v[146:149], v249
	ds_read_b128 v[150:153], v249 offset:1024
	ds_read_b128 v[164:167], v249 offset:2048
	ds_read_b128 v[168:171], v249 offset:3072
	s_cmp_eq_u32 s40, 12
	s_cselect_b32 s19, s5, s17
	s_cselect_b32 s18, s34, s16
	s_cselect_b32 s17, s3, s37
	s_cselect_b32 s16, s35, s36
	s_add_i32 s44, 0, 0x14000
	ds_read_b128 v[220:223], v249 offset:16384
	ds_read_b128 v[224:227], v249 offset:17408
	ds_read_b128 v[228:231], v249 offset:18432
	ds_read_b128 v[232:235], v249 offset:19456
	s_add_i32 m0, s9, 0xc000
	ds_read_b128 v[172:175], v163
	ds_read_b128 v[176:179], v163 offset:1024
	ds_read_b128 v[180:183], v163 offset:2048
	ds_read_b128 v[184:187], v163 offset:3072
	ds_read_b128 v[204:207], v163 offset:4096
	ds_read_b128 v[208:211], v163 offset:5120
	ds_read_b128 v[212:215], v163 offset:6144
	ds_read_b128 v[216:219], v163 offset:7168
	global_load_lds_dwordx4 v138, s[14:15]
	s_add_i32 m0, s9, 0xe000
	s_nop 0
	global_load_lds_dwordx4 v140, s[14:15]
	s_waitcnt vmcnt(8) lgkmcnt(0)
	s_barrier
	s_setprio 1
	v_mfma_f32_16x16x32_bf16 v[126:129], v[146:149], v[172:175], v[126:129]
	v_mfma_f32_16x16x32_bf16 v[122:125], v[164:167], v[172:175], v[122:125]
	v_mfma_f32_16x16x32_bf16 v[114:117], v[146:149], v[180:183], v[114:117]
	v_mfma_f32_16x16x32_bf16 v[106:109], v[164:167], v[180:183], v[106:109]
	v_mfma_f32_16x16x32_bf16 v[98:101], v[146:149], v[204:207], v[98:101]
	v_mfma_f32_16x16x32_bf16 v[90:93], v[164:167], v[204:207], v[90:93]
	v_mfma_f32_16x16x32_bf16 v[82:85], v[146:149], v[212:215], v[82:85]
	v_mfma_f32_16x16x32_bf16 v[74:77], v[164:167], v[212:215], v[74:77]
	v_mfma_f32_16x16x32_bf16 v[126:129], v[150:153], v[176:179], v[126:129]
	v_mfma_f32_16x16x32_bf16 v[122:125], v[168:171], v[176:179], v[122:125]
	v_mfma_f32_16x16x32_bf16 v[114:117], v[150:153], v[184:187], v[114:117]
	v_mfma_f32_16x16x32_bf16 v[106:109], v[168:171], v[184:187], v[106:109]
	v_mfma_f32_16x16x32_bf16 v[98:101], v[150:153], v[208:211], v[98:101]
	v_mfma_f32_16x16x32_bf16 v[90:93], v[168:171], v[208:211], v[90:93]
	v_mfma_f32_16x16x32_bf16 v[82:85], v[150:153], v[216:219], v[82:85]
	v_mfma_f32_16x16x32_bf16 v[74:77], v[168:171], v[216:219], v[74:77]
	v_mfma_f32_16x16x32_bf16 v[118:121], v[220:223], v[172:175], v[118:121]
	v_mfma_f32_16x16x32_bf16 v[110:113], v[228:231], v[172:175], v[110:113]
	v_mfma_f32_16x16x32_bf16 v[102:105], v[220:223], v[180:183], v[102:105]
	v_mfma_f32_16x16x32_bf16 v[94:97], v[228:231], v[180:183], v[94:97]
	v_mfma_f32_16x16x32_bf16 v[86:89], v[220:223], v[204:207], v[86:89]
	v_mfma_f32_16x16x32_bf16 v[78:81], v[228:231], v[204:207], v[78:81]
	v_mfma_f32_16x16x32_bf16 v[70:73], v[220:223], v[212:215], v[70:73]
	v_mfma_f32_16x16x32_bf16 v[66:69], v[228:231], v[212:215], v[66:69]
	v_mfma_f32_16x16x32_bf16 v[118:121], v[224:227], v[176:179], v[118:121]
	v_mfma_f32_16x16x32_bf16 v[110:113], v[232:235], v[176:179], v[110:113]
	v_mfma_f32_16x16x32_bf16 v[102:105], v[224:227], v[184:187], v[102:105]
	v_mfma_f32_16x16x32_bf16 v[94:97], v[232:235], v[184:187], v[94:97]
	v_mfma_f32_16x16x32_bf16 v[86:89], v[224:227], v[208:211], v[86:89]
	v_mfma_f32_16x16x32_bf16 v[78:81], v[232:235], v[208:211], v[78:81]
	v_mfma_f32_16x16x32_bf16 v[70:73], v[224:227], v[216:219], v[70:73]
	v_mfma_f32_16x16x32_bf16 v[66:69], v[232:235], v[216:219], v[66:69]
	s_setprio 0
	s_barrier
	ds_read_b128 v[172:175], v163 offset:16384
	ds_read_b128 v[176:179], v163 offset:17408
	ds_read_b128 v[180:183], v163 offset:18432
	ds_read_b128 v[184:187], v163 offset:19456
	ds_read_b128 v[204:207], v163 offset:20480
	ds_read_b128 v[208:211], v163 offset:21504
	ds_read_b128 v[212:215], v163 offset:22528
	ds_read_b128 v[216:219], v163 offset:23552
	s_add_i32 s41, s41, s25
	s_mov_b32 m0, s41
	s_nop 0
	global_load_lds_dwordx4 v132, s[16:17]
	s_add_i32 m0, s41, 0x2000
	s_nop 0
	global_load_lds_dwordx4 v136, s[16:17]
	s_mov_b32 m0, s9
	s_add_u32 s98, s18, 0x80
	s_addc_u32 s99, s19, 0
	global_load_lds_dwordx4 v130, s[18:19]
	s_mov_b32 m0, s26
	s_nop 0
	global_load_lds_dwordx4 v134, s[18:19]
	s_add_u32 s42, s16, 0x40000
	s_addc_u32 s43, s17, 0
	s_add_i32 s41, s44, s25
	s_mov_b32 m0, s41
	s_nop 0
	global_load_lds_dwordx4 v132, s[42:43]
	s_add_i32 m0, s41, 0x2000
	s_nop 0
	global_load_lds_dwordx4 v136, s[42:43]
	s_waitcnt vmcnt(8) lgkmcnt(0)
	s_barrier
	s_setprio 1
	v_mfma_f32_16x16x32_bf16 v[62:65], v[146:149], v[172:175], v[62:65]
	v_mfma_f32_16x16x32_bf16 v[58:61], v[164:167], v[172:175], v[58:61]
	v_mfma_f32_16x16x32_bf16 v[50:53], v[146:149], v[180:183], v[50:53]
	v_mfma_f32_16x16x32_bf16 v[42:45], v[164:167], v[180:183], v[42:45]
	v_mfma_f32_16x16x32_bf16 v[34:37], v[146:149], v[204:207], v[34:37]
	v_mfma_f32_16x16x32_bf16 v[26:29], v[164:167], v[204:207], v[26:29]
	v_mfma_f32_16x16x32_bf16 v[18:21], v[146:149], v[212:215], v[18:21]
	v_mfma_f32_16x16x32_bf16 v[10:13], v[164:167], v[212:215], v[10:13]
	v_mfma_f32_16x16x32_bf16 v[62:65], v[150:153], v[176:179], v[62:65]
	v_mfma_f32_16x16x32_bf16 v[58:61], v[168:171], v[176:179], v[58:61]
	v_mfma_f32_16x16x32_bf16 v[50:53], v[150:153], v[184:187], v[50:53]
	v_mfma_f32_16x16x32_bf16 v[42:45], v[168:171], v[184:187], v[42:45]
	v_mfma_f32_16x16x32_bf16 v[34:37], v[150:153], v[208:211], v[34:37]
	v_mfma_f32_16x16x32_bf16 v[26:29], v[168:171], v[208:211], v[26:29]
	v_mfma_f32_16x16x32_bf16 v[18:21], v[150:153], v[216:219], v[18:21]
	v_mfma_f32_16x16x32_bf16 v[10:13], v[168:171], v[216:219], v[10:13]
	v_mfma_f32_16x16x32_bf16 v[54:57], v[220:223], v[172:175], v[54:57]
	v_mfma_f32_16x16x32_bf16 v[46:49], v[228:231], v[172:175], v[46:49]
	v_mfma_f32_16x16x32_bf16 v[38:41], v[220:223], v[180:183], v[38:41]
	v_mfma_f32_16x16x32_bf16 v[30:33], v[228:231], v[180:183], v[30:33]
	v_mfma_f32_16x16x32_bf16 v[22:25], v[220:223], v[204:207], v[22:25]
	v_mfma_f32_16x16x32_bf16 v[14:17], v[228:231], v[204:207], v[14:17]
	v_mfma_f32_16x16x32_bf16 v[6:9], v[220:223], v[212:215], v[6:9]
	v_mfma_f32_16x16x32_bf16 v[2:5], v[228:231], v[212:215], v[2:5]
	v_mfma_f32_16x16x32_bf16 v[54:57], v[224:227], v[176:179], v[54:57]
	v_mfma_f32_16x16x32_bf16 v[46:49], v[232:235], v[176:179], v[46:49]
	v_mfma_f32_16x16x32_bf16 v[38:41], v[224:227], v[184:187], v[38:41]
	v_mfma_f32_16x16x32_bf16 v[30:33], v[232:235], v[184:187], v[30:33]
	v_mfma_f32_16x16x32_bf16 v[22:25], v[224:227], v[208:211], v[22:25]
	v_mfma_f32_16x16x32_bf16 v[14:17], v[232:235], v[208:211], v[14:17]
	v_mfma_f32_16x16x32_bf16 v[6:9], v[224:227], v[216:219], v[6:9]
	v_mfma_f32_16x16x32_bf16 v[2:5], v[232:235], v[216:219], v[2:5]
	s_setprio 0
	s_barrier
	s_add_i32 s41, 0, 0x18000
	ds_read_b128 v[146:149], v249 offset:32768
	ds_read_b128 v[150:153], v249 offset:33792
	ds_read_b128 v[164:167], v249 offset:34816
	ds_read_b128 v[168:171], v249 offset:35840
	s_add_u32 s18, s18, 0x40000
	s_addc_u32 s19, s19, 0
	s_mov_b32 m0, s27
	ds_read_b128 v[172:175], v163 offset:32768
	ds_read_b128 v[176:179], v163 offset:33792
	ds_read_b128 v[180:183], v163 offset:34816
	ds_read_b128 v[184:187], v163 offset:35840
	ds_read_b128 v[204:207], v163 offset:36864
	ds_read_b128 v[208:211], v163 offset:37888
	ds_read_b128 v[212:215], v163 offset:38912
	ds_read_b128 v[216:219], v163 offset:39936
	global_load_lds_dwordx4 v130, s[18:19]
	s_mov_b32 m0, s28
	s_nop 0
	global_load_lds_dwordx4 v134, s[18:19]
	s_add_i32 s18, 0, 0x1c000
	ds_read_b128 v[220:223], v249 offset:49152
	ds_read_b128 v[224:227], v249 offset:50176
	ds_read_b128 v[228:231], v249 offset:51200
	ds_read_b128 v[232:235], v249 offset:52224
	s_waitcnt vmcnt(8) lgkmcnt(0)
	s_barrier
	s_setprio 1
	v_mfma_f32_16x16x32_bf16 v[126:129], v[146:149], v[172:175], v[126:129]
	v_mfma_f32_16x16x32_bf16 v[122:125], v[164:167], v[172:175], v[122:125]
	v_mfma_f32_16x16x32_bf16 v[114:117], v[146:149], v[180:183], v[114:117]
	v_mfma_f32_16x16x32_bf16 v[106:109], v[164:167], v[180:183], v[106:109]
	v_mfma_f32_16x16x32_bf16 v[98:101], v[146:149], v[204:207], v[98:101]
	v_mfma_f32_16x16x32_bf16 v[90:93], v[164:167], v[204:207], v[90:93]
	v_mfma_f32_16x16x32_bf16 v[82:85], v[146:149], v[212:215], v[82:85]
	v_mfma_f32_16x16x32_bf16 v[74:77], v[164:167], v[212:215], v[74:77]
	v_mfma_f32_16x16x32_bf16 v[126:129], v[150:153], v[176:179], v[126:129]
	v_mfma_f32_16x16x32_bf16 v[122:125], v[168:171], v[176:179], v[122:125]
	v_mfma_f32_16x16x32_bf16 v[114:117], v[150:153], v[184:187], v[114:117]
	v_mfma_f32_16x16x32_bf16 v[106:109], v[168:171], v[184:187], v[106:109]
	v_mfma_f32_16x16x32_bf16 v[98:101], v[150:153], v[208:211], v[98:101]
	v_mfma_f32_16x16x32_bf16 v[90:93], v[168:171], v[208:211], v[90:93]
	v_mfma_f32_16x16x32_bf16 v[82:85], v[150:153], v[216:219], v[82:85]
	v_mfma_f32_16x16x32_bf16 v[74:77], v[168:171], v[216:219], v[74:77]
	v_mfma_f32_16x16x32_bf16 v[118:121], v[220:223], v[172:175], v[118:121]
	v_mfma_f32_16x16x32_bf16 v[110:113], v[228:231], v[172:175], v[110:113]
	v_mfma_f32_16x16x32_bf16 v[102:105], v[220:223], v[180:183], v[102:105]
	v_mfma_f32_16x16x32_bf16 v[94:97], v[228:231], v[180:183], v[94:97]
	v_mfma_f32_16x16x32_bf16 v[86:89], v[220:223], v[204:207], v[86:89]
	v_mfma_f32_16x16x32_bf16 v[78:81], v[228:231], v[204:207], v[78:81]
	v_mfma_f32_16x16x32_bf16 v[70:73], v[220:223], v[212:215], v[70:73]
	v_mfma_f32_16x16x32_bf16 v[66:69], v[228:231], v[212:215], v[66:69]
	v_mfma_f32_16x16x32_bf16 v[118:121], v[224:227], v[176:179], v[118:121]
	v_mfma_f32_16x16x32_bf16 v[110:113], v[232:235], v[176:179], v[110:113]
	v_mfma_f32_16x16x32_bf16 v[102:105], v[224:227], v[184:187], v[102:105]
	v_mfma_f32_16x16x32_bf16 v[94:97], v[232:235], v[184:187], v[94:97]
	v_mfma_f32_16x16x32_bf16 v[86:89], v[224:227], v[208:211], v[86:89]
	v_mfma_f32_16x16x32_bf16 v[78:81], v[232:235], v[208:211], v[78:81]
	v_mfma_f32_16x16x32_bf16 v[70:73], v[224:227], v[216:219], v[70:73]
	v_mfma_f32_16x16x32_bf16 v[66:69], v[232:235], v[216:219], v[66:69]
	s_setprio 0
	s_barrier
	ds_read_b128 v[172:175], v163 offset:49152
	ds_read_b128 v[176:179], v163 offset:50176
	ds_read_b128 v[180:183], v163 offset:51200
	ds_read_b128 v[184:187], v163 offset:52224
	ds_read_b128 v[204:207], v163 offset:53248
	ds_read_b128 v[208:211], v163 offset:54272
	ds_read_b128 v[212:215], v163 offset:55296
	ds_read_b128 v[216:219], v163 offset:56320
	s_add_i32 s19, s41, s25
	s_mov_b32 m0, s19
	s_add_u32 vcc_lo, s16, 0x80
	s_addc_u32 vcc_hi, s17, 0
	global_load_lds_dwordx4 v132, vcc
	s_add_i32 m0, s19, 0x2000
	s_nop 0
	global_load_lds_dwordx4 v136, vcc
	s_mov_b32 m0, s29
	s_nop 0
	global_load_lds_dwordx4 v130, s[98:99]
	s_mov_b32 m0, s30
	s_nop 0
	global_load_lds_dwordx4 v134, s[98:99]
	s_add_u32 s16, s16, 0x40080
	s_addc_u32 s17, s17, 0
	s_add_i32 s18, s18, s25
	s_mov_b32 m0, s18
	s_nop 0
	global_load_lds_dwordx4 v132, s[16:17]
	s_add_i32 m0, s18, 0x2000
	s_nop 0
	global_load_lds_dwordx4 v136, s[16:17]
	s_add_i32 s40, s40, 2
	s_add_u32 s14, s14, 0x100
	s_addc_u32 s15, s15, 0
	s_add_u32 s36, s36, 0x100
	s_addc_u32 s37, s37, 0
	s_cmp_gt_u32 s40, 13
	s_waitcnt vmcnt(8) lgkmcnt(0)
	s_barrier
	s_setprio 1
	v_mfma_f32_16x16x32_bf16 v[62:65], v[146:149], v[172:175], v[62:65]
	v_mfma_f32_16x16x32_bf16 v[58:61], v[164:167], v[172:175], v[58:61]
	v_mfma_f32_16x16x32_bf16 v[50:53], v[146:149], v[180:183], v[50:53]
	v_mfma_f32_16x16x32_bf16 v[42:45], v[164:167], v[180:183], v[42:45]
	v_mfma_f32_16x16x32_bf16 v[34:37], v[146:149], v[204:207], v[34:37]
	v_mfma_f32_16x16x32_bf16 v[26:29], v[164:167], v[204:207], v[26:29]
	v_mfma_f32_16x16x32_bf16 v[18:21], v[146:149], v[212:215], v[18:21]
	v_mfma_f32_16x16x32_bf16 v[10:13], v[164:167], v[212:215], v[10:13]
	v_mfma_f32_16x16x32_bf16 v[62:65], v[150:153], v[176:179], v[62:65]
	v_mfma_f32_16x16x32_bf16 v[58:61], v[168:171], v[176:179], v[58:61]
	v_mfma_f32_16x16x32_bf16 v[50:53], v[150:153], v[184:187], v[50:53]
	v_mfma_f32_16x16x32_bf16 v[42:45], v[168:171], v[184:187], v[42:45]
	v_mfma_f32_16x16x32_bf16 v[34:37], v[150:153], v[208:211], v[34:37]
	v_mfma_f32_16x16x32_bf16 v[26:29], v[168:171], v[208:211], v[26:29]
	v_mfma_f32_16x16x32_bf16 v[18:21], v[150:153], v[216:219], v[18:21]
	v_mfma_f32_16x16x32_bf16 v[10:13], v[168:171], v[216:219], v[10:13]
	v_mfma_f32_16x16x32_bf16 v[54:57], v[220:223], v[172:175], v[54:57]
	v_mfma_f32_16x16x32_bf16 v[46:49], v[228:231], v[172:175], v[46:49]
	v_mfma_f32_16x16x32_bf16 v[38:41], v[220:223], v[180:183], v[38:41]
	v_mfma_f32_16x16x32_bf16 v[30:33], v[228:231], v[180:183], v[30:33]
	v_mfma_f32_16x16x32_bf16 v[22:25], v[220:223], v[204:207], v[22:25]
	v_mfma_f32_16x16x32_bf16 v[14:17], v[228:231], v[204:207], v[14:17]
	v_mfma_f32_16x16x32_bf16 v[6:9], v[220:223], v[212:215], v[6:9]
	v_mfma_f32_16x16x32_bf16 v[2:5], v[228:231], v[212:215], v[2:5]
	v_mfma_f32_16x16x32_bf16 v[54:57], v[224:227], v[176:179], v[54:57]
	v_mfma_f32_16x16x32_bf16 v[46:49], v[232:235], v[176:179], v[46:49]
	v_mfma_f32_16x16x32_bf16 v[38:41], v[224:227], v[184:187], v[38:41]
	v_mfma_f32_16x16x32_bf16 v[30:33], v[232:235], v[184:187], v[30:33]
	v_mfma_f32_16x16x32_bf16 v[22:25], v[224:227], v[208:211], v[22:25]
	v_mfma_f32_16x16x32_bf16 v[14:17], v[232:235], v[208:211], v[14:17]
	v_mfma_f32_16x16x32_bf16 v[6:9], v[224:227], v[216:219], v[6:9]
	v_mfma_f32_16x16x32_bf16 v[2:5], v[232:235], v[216:219], v[2:5]
	s_setprio 0
	s_barrier
	s_cbranch_scc0 .LBB0_1156
	s_mov_b64 s[14:15], -1
	s_cmp_gt_i32 s6, 5
	v_lshl_add_u32 v143, s7, 8, v145
	s_cbranch_scc0 .LBB0_1175
	v_lshl_add_u32 v144, v143, 2, 0
	v_add_u32_e32 v164, 0x20040, v144
	ds_read_b32 v144, v164
	s_cmp_gt_u32 s6, 7
	s_cselect_b64 s[14:15], -1, 0
	s_cmp_lt_u32 s6, 8
	s_waitcnt lgkmcnt(0)
	v_pk_mul_f32 v[146:147], v[122:123], v[144:145] op_sel_hi:[1,0]
	v_pk_mul_f32 v[152:153], v[124:125], v[144:145] op_sel_hi:[1,0]
	v_pk_mul_f32 v[148:149], v[110:111], v[144:145] op_sel_hi:[1,0]
	v_pk_mul_f32 v[150:151], v[112:113], v[144:145] op_sel_hi:[1,0]
	s_cbranch_scc1 .LBB0_1160
	v_mul_f32_e32 v146, 0xbfb8aa3b, v146
	v_mul_f32_e32 v147, 0xbfb8aa3b, v147
	v_mul_f32_e32 v152, 0xbfb8aa3b, v152
	v_mul_f32_e32 v153, 0xbfb8aa3b, v153
	v_mul_f32_e32 v148, 0xbfb8aa3b, v148
	v_mul_f32_e32 v149, 0xbfb8aa3b, v149
	v_mul_f32_e32 v150, 0xbfb8aa3b, v150
	v_mul_f32_e32 v151, 0xbfb8aa3b, v151
	v_exp_f32_e32 v146, v146
	v_exp_f32_e32 v147, v147
	v_exp_f32_e32 v152, v152
	v_exp_f32_e32 v153, v153
	v_exp_f32_e32 v148, v148
	v_exp_f32_e32 v149, v149
	v_exp_f32_e32 v150, v150
	v_exp_f32_e32 v151, v151
	v_add_f32_e32 v146, 1.0, v146
	v_add_f32_e32 v147, 1.0, v147
	v_add_f32_e32 v152, 1.0, v152
	v_add_f32_e32 v153, 1.0, v153
	v_add_f32_e32 v148, 1.0, v148
	v_add_f32_e32 v149, 1.0, v149
	v_add_f32_e32 v150, 1.0, v150
	v_add_f32_e32 v151, 1.0, v151
	v_rcp_f32_e32 v146, v146
	v_rcp_f32_e32 v147, v147
	v_rcp_f32_e32 v152, v152
	v_rcp_f32_e32 v153, v153
	v_rcp_f32_e32 v148, v148
	v_rcp_f32_e32 v149, v149
	v_rcp_f32_e32 v150, v150
	v_rcp_f32_e32 v151, v151
